# U (branch output, OUTPROJ A operand) stored K-blocked
# speedup vs baseline: 1.0761x; 1.0033x over previous
; DI int TID() { int t = (int)__builtin_amdgcn_workitem_id_x(); asm volatile("" : "+v"(t)); return t; }
; #define BLOAD(A_, B_, kt) do { _Pragma("unroll") for (int i = 0; i < 4; ++i) { \
;     A_[i] = *(const u32x4*)((const char*)Ap + (aoff + (unsigned)(32 * i * lda + (kt) * 64) * 2u)); B_[i] = *(const u32x4*)((const char*)Wt + (woff + (unsigned)(32 * i * K + (kt) * 64) * 2u)); } } while (0)
; #define BLOAD(A_, B_, kt) do { _Pragma("unroll") for (int i = 0; i < 4; ++i) { \
;     A_[i] = *(const u32x4*)((const char*)Ap + (aoff + (unsigned)(32 * i * lda + (kt) * 64) * 2u)); B_[i] = *(const u32x4*)((const char*)Wt + (woff + (unsigned)(32 * i * K + (kt) * 64) * 2u)); } } while (0)
; #define BSTORE(A_, B_, buf) do { _Pragma("unroll") for (int i = 0; i < 4; ++i) { \
;     *(u32x4*)&As[(buf) * GBUF + (srow + 32 * i) * LDT + sc8] = A_[i]; \
;     *(u32x4*)&Bs[(buf) * GBUF + (srow + 32 * i) * LDT + sc8] = B_[i]; } } while (0)
; template <int NK>
; DI void gemm_run(PF& pf, const u16* __restrict__ Ap, int lda, const u16* __restrict__ Wt, f32x16 (&acc)[2][2], char* smem) {
;     ...
;   __builtin_amdgcn_s_setprio(0);
;   __syncthreads();
;   BSTORE(pf.a0, pf.b0, 0);
;   BLOAD(pf.a0, pf.b0, 2);
;   __syncthreads();
; DI void tile_outproj(const Params& p, int l, const Chunk& ck, int tile, int next, PF& pf, char* smem) {
;   float* Cs = (float*)smem;
;   const int tid = TID(); const int mi = tile & (MTN - 1), ni = tile >> MTS; const int m0 = mi * 128, n0 = ni * 128;
;   f32x16 acc[2][2]; zero_acc(acc);
;   { const u16* Ap; const u16* Wt; outproj_ptrs(p, l, tile, Ap, Wt); gemm_run<16>(pf, Ap, 1024, Wt, acc, smem); }
.LBB1_255:
	s_add_i32 s41, s35, s78
	s_cmpk_gt_i32 s41, 0x1ff
	s_cselect_b64 s[24:25], -1, 0
	s_cmpk_lt_i32 s41, 0x200
	s_cselect_b32 s0, s41, -1
	s_and_b32 s27, s34, 0xfe0000
	s_and_b32 s26, s35, 0xffffff80
	s_lshl_b32 s26, s26, 1
	s_lshr_b32 s27, s27, 4
	s_add_u32 s28, s16, s27
	v_mov_b32_e32 v0, v172
	s_addc_u32 s29, s17, 0
	s_ashr_i32 s27, s26, 31
	s_lshl_b64 s[30:31], s[26:27], 6
	s_add_u32 s30, s36, s30
	s_addc_u32 s31, s37, s31
	s_setprio 0
	s_waitcnt lgkmcnt(0)
	v_and_b32_e32 v150, 63, v172
	v_lshrrev_b32_e32 v151, 6, v172
	v_bfe_u32 v152, v150, 4, 2
	v_lshrrev_b32_e32 v153, 1, v152
	v_xor_b32_e32 v152, v152, v153
	v_and_b32_e32 v152, 1, v152
	v_lshl_or_b32 v152, v152, 1, v153
	v_xor_b32_e32 v152, v152, v150
	v_and_b32_e32 v152, 3, v152
	v_lshlrev_b32_e32 v152, 4, v152
	v_lshrrev_b32_e32 v153, 2, v150
	v_lshl_add_u32 v143, v151, 5, v153
	v_lshl_add_u32 v143, v143, 6, v152
	v_mov_b32_e32 v144, v143
	v_lshl_add_u32 v145, v151, 6, v153
	v_lshl_add_u32 v145, v145, 6, v152
	v_mov_b32_e32 v146, v145
	v_mov_b32_e32 v147, v145
	v_mov_b32_e32 v148, v145
	v_readfirstlane_b32 s42, v151
	s_lshl_b32 s43, s42, 12
	s_lshl_b32 s42, s42, 11
	s_add_u32 s43, s43, 0x2000
	v_bfe_u32 v152, v150, 2, 2
	v_lshrrev_b32_e32 v153, 1, v152
	v_xor_b32_e32 v152, v152, v153
	v_and_b32_e32 v152, 1, v152
	v_lshl_or_b32 v152, v152, 1, v153
	v_lshrrev_b32_e32 v153, 4, v150
	v_xor_b32_e32 v152, v152, v153
	v_lshlrev_b32_e32 v152, 4, v152
	v_and_b32_e32 v150, 15, v150
	v_lshl_add_u32 v150, v150, 6, v152
	v_lshrrev_b32_e32 v152, 1, v151
	v_and_b32_e32 v153, 1, v151
	v_lshl_add_u32 v126, v152, 12, v150
	v_lshl_add_u32 v128, v153, 12, v150
	v_add_u32_e32 v128, 0x2000, v128
	s_barrier
	v_mov_b32_e32 v2, 0
	v_mov_b32_e32 v3, 0
	v_mov_b32_e32 v4, 0
	v_mov_b32_e32 v5, 0
	v_mov_b32_e32 v6, 0
	v_mov_b32_e32 v7, 0
	v_mov_b32_e32 v8, 0
	v_mov_b32_e32 v9, 0
	v_mov_b32_e32 v10, 0
	v_mov_b32_e32 v11, 0
	v_mov_b32_e32 v12, 0
	v_mov_b32_e32 v13, 0
	v_mov_b32_e32 v14, 0
	v_mov_b32_e32 v15, 0
	v_mov_b32_e32 v16, 0
	v_mov_b32_e32 v17, 0
	v_mov_b32_e32 v18, 0
	v_mov_b32_e32 v19, 0
	v_mov_b32_e32 v20, 0
	v_mov_b32_e32 v21, 0
	v_mov_b32_e32 v22, 0
	v_mov_b32_e32 v23, 0
	v_mov_b32_e32 v24, 0
	v_mov_b32_e32 v25, 0
	v_mov_b32_e32 v26, 0
	v_mov_b32_e32 v27, 0
	v_mov_b32_e32 v28, 0
	v_mov_b32_e32 v29, 0
	v_mov_b32_e32 v30, 0
	v_mov_b32_e32 v31, 0
	v_mov_b32_e32 v32, 0
	v_mov_b32_e32 v33, 0
	v_mov_b32_e32 v34, 0
	v_mov_b32_e32 v35, 0
	v_mov_b32_e32 v36, 0
	v_mov_b32_e32 v37, 0
	v_mov_b32_e32 v38, 0
	v_mov_b32_e32 v39, 0
	v_mov_b32_e32 v40, 0
	v_mov_b32_e32 v41, 0
	v_mov_b32_e32 v42, 0
	v_mov_b32_e32 v43, 0
	v_mov_b32_e32 v44, 0
	v_mov_b32_e32 v45, 0
	v_mov_b32_e32 v46, 0
	v_mov_b32_e32 v47, 0
	v_mov_b32_e32 v48, 0
	v_mov_b32_e32 v49, 0
	v_mov_b32_e32 v50, 0
	v_mov_b32_e32 v51, 0
	v_mov_b32_e32 v52, 0
	v_mov_b32_e32 v53, 0
	v_mov_b32_e32 v54, 0
	v_mov_b32_e32 v55, 0
	v_mov_b32_e32 v56, 0
	v_mov_b32_e32 v57, 0
	v_mov_b32_e32 v58, 0
	v_mov_b32_e32 v59, 0
	v_mov_b32_e32 v60, 0
	v_mov_b32_e32 v61, 0
	v_mov_b32_e32 v62, 0
	v_mov_b32_e32 v63, 0
	v_mov_b32_e32 v64, 0
	v_mov_b32_e32 v65, 0
	v_mov_b32_e32 v74, 0
	v_mov_b32_e32 v75, 0
	v_mov_b32_e32 v76, 0
	v_mov_b32_e32 v77, 0
	v_mov_b32_e32 v78, 0
	v_mov_b32_e32 v79, 0
	v_mov_b32_e32 v80, 0
	v_mov_b32_e32 v81, 0
	v_mov_b32_e32 v82, 0
	v_mov_b32_e32 v83, 0
	v_mov_b32_e32 v84, 0
	v_mov_b32_e32 v85, 0
	v_mov_b32_e32 v86, 0
	v_mov_b32_e32 v87, 0
	v_mov_b32_e32 v88, 0
	v_mov_b32_e32 v89, 0
	v_mov_b32_e32 v90, 0
	v_mov_b32_e32 v91, 0
	v_mov_b32_e32 v92, 0
	v_mov_b32_e32 v93, 0
	v_mov_b32_e32 v94, 0
	v_mov_b32_e32 v95, 0
	v_mov_b32_e32 v96, 0
	v_mov_b32_e32 v97, 0
	v_mov_b32_e32 v98, 0
	v_mov_b32_e32 v99, 0
	v_mov_b32_e32 v100, 0
	v_mov_b32_e32 v101, 0
	v_mov_b32_e32 v102, 0
	v_mov_b32_e32 v103, 0
	v_mov_b32_e32 v104, 0
	v_mov_b32_e32 v105, 0
	v_mov_b32_e32 v106, 0
	v_mov_b32_e32 v107, 0
	v_mov_b32_e32 v108, 0
	v_mov_b32_e32 v109, 0
	v_mov_b32_e32 v110, 0
	v_mov_b32_e32 v111, 0
	v_mov_b32_e32 v112, 0
	v_mov_b32_e32 v113, 0
	v_mov_b32_e32 v114, 0
	v_mov_b32_e32 v115, 0
	v_mov_b32_e32 v116, 0
	v_mov_b32_e32 v117, 0
	v_mov_b32_e32 v118, 0
	v_mov_b32_e32 v119, 0
	v_mov_b32_e32 v120, 0
	v_mov_b32_e32 v121, 0
	v_mov_b32_e32 v208, 0
	v_mov_b32_e32 v209, 0
	v_mov_b32_e32 v210, 0
	v_mov_b32_e32 v211, 0
	v_mov_b32_e32 v212, 0
	v_mov_b32_e32 v213, 0
	v_mov_b32_e32 v214, 0
	v_mov_b32_e32 v215, 0
	v_mov_b32_e32 v216, 0
	v_mov_b32_e32 v217, 0
	v_mov_b32_e32 v218, 0
	v_mov_b32_e32 v219, 0
	v_mov_b32_e32 v220, 0
	v_mov_b32_e32 v221, 0
	v_mov_b32_e32 v222, 0
	v_mov_b32_e32 v223, 0
	s_add_u32 m0, s42, 0x0
	s_nop 0
	global_load_lds_dwordx4 v143, s[28:29]
	global_load_lds_dwordx4 v144, s[28:29] offset:1024
	s_add_u32 m0, s43, 0x0
	s_nop 0
	global_load_lds_dwordx4 v145, s[30:31]
	global_load_lds_dwordx4 v146, s[30:31] offset:1024
	global_load_lds_dwordx4 v147, s[30:31] offset:2048
	global_load_lds_dwordx4 v148, s[30:31] offset:3072
	s_add_u32 m0, s42, 0x6000
	s_add_u32 s28, s28, 0x100000
	s_addc_u32 s29, s29, 0
	global_load_lds_dwordx4 v143, s[28:29]
	global_load_lds_dwordx4 v144, s[28:29] offset:1024
	s_add_u32 m0, s43, 0x6000
	s_add_u32 s30, s30, 0x10000
	s_addc_u32 s31, s31, 0
	global_load_lds_dwordx4 v145, s[30:31]
	global_load_lds_dwordx4 v146, s[30:31] offset:1024
	global_load_lds_dwordx4 v147, s[30:31] offset:2048
	global_load_lds_dwordx4 v148, s[30:31] offset:3072
	s_mov_b32 s46, 10
; #define BLOAD(A_, B_, kt) do { _Pragma("unroll") for (int i = 0; i < 4; ++i) { \
;     A_[i] = *(const u32x4*)((const char*)Ap + (aoff + (unsigned)(32 * i * lda + (kt) * 64) * 2u)); B_[i] = *(const u32x4*)((const char*)Wt + (woff + (unsigned)(32 * i * K + (kt) * 64) * 2u)); } } while (0)
; #define BLOAD(A_, B_, kt) do { _Pragma("unroll") for (int i = 0; i < 4; ++i) { \
;     A_[i] = *(const u32x4*)((const char*)Ap + (aoff + (unsigned)(32 * i * lda + (kt) * 64) * 2u)); B_[i] = *(const u32x4*)((const char*)Wt + (woff + (unsigned)(32 * i * K + (kt) * 64) * 2u)); } } while (0)
; #define BSTORE(A_, B_, buf) do { _Pragma("unroll") for (int i = 0; i < 4; ++i) { \
;     *(u32x4*)&As[(buf) * GBUF + (srow + 32 * i) * LDT + sc8] = A_[i]; \
;     *(u32x4*)&Bs[(buf) * GBUF + (srow + 32 * i) * LDT + sc8] = B_[i]; } } while (0)
; template <int NK>
; DI void gemm_run(PF& pf, const u16* __restrict__ Ap, int lda, const u16* __restrict__ Wt, f32x16 (&acc)[2][2], char* smem) {
;     ...
; #pragma unroll
;   for (int kt = 0; kt < nk; kt += 2) {
;     BCOMP(0);
;     BSTORE(pf.a1, pf.b1, 1);
;     if (kt + 3 < nk) BLOAD(pf.a1, pf.b1, kt + 3);
;     __syncthreads();
;     BCOMP(1);
;     if (kt + 2 < nk) { BSTORE(pf.a0, pf.b0, 0); if (kt + 4 < nk) BLOAD(pf.a0, pf.b0, kt + 4); }
;     __syncthreads();
;   }
.Lout_kloop:
	s_waitcnt vmcnt(6)
	s_barrier
	ds_read_b128 v[224:227], v126 offset:0
	ds_read_b128 v[240:243], v128 offset:0
	ds_read_b128 v[244:247], v128 offset:1024
	ds_read_b128 v[248:251], v128 offset:2048
	ds_read_b128 v[156:159], v128 offset:3072
	s_add_u32 m0, s42, 0xc000
	s_add_u32 s28, s28, 0x100000
	s_addc_u32 s29, s29, 0
	global_load_lds_dwordx4 v143, s[28:29]
	global_load_lds_dwordx4 v144, s[28:29] offset:1024
	s_add_u32 m0, s43, 0xc000
	s_add_u32 s30, s30, 0x10000
	s_addc_u32 s31, s31, 0
	global_load_lds_dwordx4 v145, s[30:31]
	global_load_lds_dwordx4 v146, s[30:31] offset:1024
	global_load_lds_dwordx4 v147, s[30:31] offset:2048
	global_load_lds_dwordx4 v148, s[30:31] offset:3072
	ds_read_b128 v[228:231], v126 offset:1024
	ds_read_b128 v[232:235], v126 offset:2048
	ds_read_b128 v[236:239], v126 offset:3072
	ds_read_b128 v[160:163], v128 offset:8192
	ds_read_b128 v[164:167], v128 offset:9216
	ds_read_b128 v[168:171], v128 offset:10240
	ds_read_b128 v[122:125], v128 offset:11264
	s_waitcnt lgkmcnt(10)
	v_mfma_f32_16x16x32_bf16 v[2:5], v[240:243], v[224:227], v[2:5]
	s_waitcnt lgkmcnt(9)
	v_mfma_f32_16x16x32_bf16 v[6:9], v[244:247], v[224:227], v[6:9]
	s_waitcnt lgkmcnt(8)
	v_mfma_f32_16x16x32_bf16 v[10:13], v[248:251], v[224:227], v[10:13]
	s_waitcnt lgkmcnt(7)
	v_mfma_f32_16x16x32_bf16 v[14:17], v[156:159], v[224:227], v[14:17]
	s_waitcnt lgkmcnt(6)
	v_mfma_f32_16x16x32_bf16 v[18:21], v[240:243], v[228:231], v[18:21]
	v_mfma_f32_16x16x32_bf16 v[22:25], v[244:247], v[228:231], v[22:25]
	v_mfma_f32_16x16x32_bf16 v[26:29], v[248:251], v[228:231], v[26:29]
	v_mfma_f32_16x16x32_bf16 v[30:33], v[156:159], v[228:231], v[30:33]
	s_waitcnt lgkmcnt(5)
	v_mfma_f32_16x16x32_bf16 v[34:37], v[240:243], v[232:235], v[34:37]
	v_mfma_f32_16x16x32_bf16 v[38:41], v[244:247], v[232:235], v[38:41]
	v_mfma_f32_16x16x32_bf16 v[42:45], v[248:251], v[232:235], v[42:45]
	v_mfma_f32_16x16x32_bf16 v[46:49], v[156:159], v[232:235], v[46:49]
	s_waitcnt lgkmcnt(4)
	v_mfma_f32_16x16x32_bf16 v[50:53], v[240:243], v[236:239], v[50:53]
	v_mfma_f32_16x16x32_bf16 v[54:57], v[244:247], v[236:239], v[54:57]
	v_mfma_f32_16x16x32_bf16 v[58:61], v[248:251], v[236:239], v[58:61]
	v_mfma_f32_16x16x32_bf16 v[62:65], v[156:159], v[236:239], v[62:65]
	s_waitcnt lgkmcnt(3)
	v_mfma_f32_16x16x32_bf16 v[74:77], v[160:163], v[224:227], v[74:77]
	s_waitcnt lgkmcnt(2)
	v_mfma_f32_16x16x32_bf16 v[78:81], v[164:167], v[224:227], v[78:81]
	s_waitcnt lgkmcnt(1)
	v_mfma_f32_16x16x32_bf16 v[82:85], v[168:171], v[224:227], v[82:85]
	s_waitcnt lgkmcnt(0)
	v_mfma_f32_16x16x32_bf16 v[86:89], v[122:125], v[224:227], v[86:89]
	v_mfma_f32_16x16x32_bf16 v[90:93], v[160:163], v[228:231], v[90:93]
	v_mfma_f32_16x16x32_bf16 v[94:97], v[164:167], v[228:231], v[94:97]
	v_mfma_f32_16x16x32_bf16 v[98:101], v[168:171], v[228:231], v[98:101]
	v_mfma_f32_16x16x32_bf16 v[102:105], v[122:125], v[228:231], v[102:105]
	v_mfma_f32_16x16x32_bf16 v[106:109], v[160:163], v[232:235], v[106:109]
	v_mfma_f32_16x16x32_bf16 v[110:113], v[164:167], v[232:235], v[110:113]
	v_mfma_f32_16x16x32_bf16 v[114:117], v[168:171], v[232:235], v[114:117]
	v_mfma_f32_16x16x32_bf16 v[118:121], v[122:125], v[232:235], v[118:121]
	v_mfma_f32_16x16x32_bf16 v[208:211], v[160:163], v[236:239], v[208:211]
	v_mfma_f32_16x16x32_bf16 v[212:215], v[164:167], v[236:239], v[212:215]
	v_mfma_f32_16x16x32_bf16 v[216:219], v[168:171], v[236:239], v[216:219]
	v_mfma_f32_16x16x32_bf16 v[220:223], v[122:125], v[236:239], v[220:223]
	s_waitcnt vmcnt(6)
	s_barrier
	ds_read_b128 v[224:227], v126 offset:24576
	ds_read_b128 v[240:243], v128 offset:24576
	ds_read_b128 v[244:247], v128 offset:25600
	ds_read_b128 v[248:251], v128 offset:26624
	ds_read_b128 v[156:159], v128 offset:27648
	s_add_u32 m0, s42, 0x0
	s_add_u32 s28, s28, 0x100000
	s_addc_u32 s29, s29, 0
	global_load_lds_dwordx4 v143, s[28:29]
	global_load_lds_dwordx4 v144, s[28:29] offset:1024
	s_add_u32 m0, s43, 0x0
	s_add_u32 s30, s30, 0x10000
	s_addc_u32 s31, s31, 0
	global_load_lds_dwordx4 v145, s[30:31]
	global_load_lds_dwordx4 v146, s[30:31] offset:1024
	global_load_lds_dwordx4 v147, s[30:31] offset:2048
	global_load_lds_dwordx4 v148, s[30:31] offset:3072
	ds_read_b128 v[228:231], v126 offset:25600
	ds_read_b128 v[232:235], v126 offset:26624
	ds_read_b128 v[236:239], v126 offset:27648
	ds_read_b128 v[160:163], v128 offset:32768
	ds_read_b128 v[164:167], v128 offset:33792
	ds_read_b128 v[168:171], v128 offset:34816
	ds_read_b128 v[122:125], v128 offset:35840
	s_waitcnt lgkmcnt(10)
	v_mfma_f32_16x16x32_bf16 v[2:5], v[240:243], v[224:227], v[2:5]
	s_waitcnt lgkmcnt(9)
	v_mfma_f32_16x16x32_bf16 v[6:9], v[244:247], v[224:227], v[6:9]
	s_waitcnt lgkmcnt(8)
	v_mfma_f32_16x16x32_bf16 v[10:13], v[248:251], v[224:227], v[10:13]
	s_waitcnt lgkmcnt(7)
	v_mfma_f32_16x16x32_bf16 v[14:17], v[156:159], v[224:227], v[14:17]
	s_waitcnt lgkmcnt(6)
	v_mfma_f32_16x16x32_bf16 v[18:21], v[240:243], v[228:231], v[18:21]
	v_mfma_f32_16x16x32_bf16 v[22:25], v[244:247], v[228:231], v[22:25]
	v_mfma_f32_16x16x32_bf16 v[26:29], v[248:251], v[228:231], v[26:29]
	v_mfma_f32_16x16x32_bf16 v[30:33], v[156:159], v[228:231], v[30:33]
	s_waitcnt lgkmcnt(5)
	v_mfma_f32_16x16x32_bf16 v[34:37], v[240:243], v[232:235], v[34:37]
	v_mfma_f32_16x16x32_bf16 v[38:41], v[244:247], v[232:235], v[38:41]
	v_mfma_f32_16x16x32_bf16 v[42:45], v[248:251], v[232:235], v[42:45]
	v_mfma_f32_16x16x32_bf16 v[46:49], v[156:159], v[232:235], v[46:49]
	s_waitcnt lgkmcnt(4)
	v_mfma_f32_16x16x32_bf16 v[50:53], v[240:243], v[236:239], v[50:53]
	v_mfma_f32_16x16x32_bf16 v[54:57], v[244:247], v[236:239], v[54:57]
	v_mfma_f32_16x16x32_bf16 v[58:61], v[248:251], v[236:239], v[58:61]
	v_mfma_f32_16x16x32_bf16 v[62:65], v[156:159], v[236:239], v[62:65]
	s_waitcnt lgkmcnt(3)
	v_mfma_f32_16x16x32_bf16 v[74:77], v[160:163], v[224:227], v[74:77]
	s_waitcnt lgkmcnt(2)
	v_mfma_f32_16x16x32_bf16 v[78:81], v[164:167], v[224:227], v[78:81]
	s_waitcnt lgkmcnt(1)
	v_mfma_f32_16x16x32_bf16 v[82:85], v[168:171], v[224:227], v[82:85]
	s_waitcnt lgkmcnt(0)
	v_mfma_f32_16x16x32_bf16 v[86:89], v[122:125], v[224:227], v[86:89]
	v_mfma_f32_16x16x32_bf16 v[90:93], v[160:163], v[228:231], v[90:93]
	v_mfma_f32_16x16x32_bf16 v[94:97], v[164:167], v[228:231], v[94:97]
	v_mfma_f32_16x16x32_bf16 v[98:101], v[168:171], v[228:231], v[98:101]
	v_mfma_f32_16x16x32_bf16 v[102:105], v[122:125], v[228:231], v[102:105]
	v_mfma_f32_16x16x32_bf16 v[106:109], v[160:163], v[232:235], v[106:109]
	v_mfma_f32_16x16x32_bf16 v[110:113], v[164:167], v[232:235], v[110:113]
	v_mfma_f32_16x16x32_bf16 v[114:117], v[168:171], v[232:235], v[114:117]
	v_mfma_f32_16x16x32_bf16 v[118:121], v[122:125], v[232:235], v[118:121]
	v_mfma_f32_16x16x32_bf16 v[208:211], v[160:163], v[236:239], v[208:211]
	v_mfma_f32_16x16x32_bf16 v[212:215], v[164:167], v[236:239], v[212:215]
	v_mfma_f32_16x16x32_bf16 v[216:219], v[168:171], v[236:239], v[216:219]
	v_mfma_f32_16x16x32_bf16 v[220:223], v[122:125], v[236:239], v[220:223]
	s_waitcnt vmcnt(6)
	s_barrier
; #define BLOAD(A_, B_, kt) do { _Pragma("unroll") for (int i = 0; i < 4; ++i) { \
;     A_[i] = *(const u32x4*)((const char*)Ap + (aoff + (unsigned)(32 * i * lda + (kt) * 64) * 2u)); B_[i] = *(const u32x4*)((const char*)Wt + (woff + (unsigned)(32 * i * K + (kt) * 64) * 2u)); } } while (0)
; #define BLOAD(A_, B_, kt) do { _Pragma("unroll") for (int i = 0; i < 4; ++i) { \
;     A_[i] = *(const u32x4*)((const char*)Ap + (aoff + (unsigned)(32 * i * lda + (kt) * 64) * 2u)); B_[i] = *(const u32x4*)((const char*)Wt + (woff + (unsigned)(32 * i * K + (kt) * 64) * 2u)); } } while (0)
; #define BSTORE(A_, B_, buf) do { _Pragma("unroll") for (int i = 0; i < 4; ++i) { \
;     *(u32x4*)&As[(buf) * GBUF + (srow + 32 * i) * LDT + sc8] = A_[i]; \
;     *(u32x4*)&Bs[(buf) * GBUF + (srow + 32 * i) * LDT + sc8] = B_[i]; } } while (0)
; template <int NK>
; DI void gemm_run(PF& pf, const u16* __restrict__ Ap, int lda, const u16* __restrict__ Wt, f32x16 (&acc)[2][2], char* smem) {
;     ...
; #pragma unroll
;   for (int kt = 0; kt < nk; kt += 2) {
;     BCOMP(0);
;     BSTORE(pf.a1, pf.b1, 1);
;     if (kt + 3 < nk) BLOAD(pf.a1, pf.b1, kt + 3);
;     __syncthreads();
;     BCOMP(1);
;     if (kt + 2 < nk) { BSTORE(pf.a0, pf.b0, 0); if (kt + 4 < nk) BLOAD(pf.a0, pf.b0, kt + 4); }
;     __syncthreads();
;   }
	ds_read_b128 v[224:227], v126 offset:49152
	ds_read_b128 v[240:243], v128 offset:49152
	ds_read_b128 v[244:247], v128 offset:50176
	ds_read_b128 v[248:251], v128 offset:51200
	ds_read_b128 v[156:159], v128 offset:52224
	s_add_u32 m0, s42, 0x6000
	s_add_u32 s28, s28, 0x100000
	s_addc_u32 s29, s29, 0
	global_load_lds_dwordx4 v143, s[28:29]
	global_load_lds_dwordx4 v144, s[28:29] offset:1024
	s_add_u32 m0, s43, 0x6000
	s_add_u32 s30, s30, 0x10000
	s_addc_u32 s31, s31, 0
	global_load_lds_dwordx4 v145, s[30:31]
	global_load_lds_dwordx4 v146, s[30:31] offset:1024
	global_load_lds_dwordx4 v147, s[30:31] offset:2048
	global_load_lds_dwordx4 v148, s[30:31] offset:3072
	ds_read_b128 v[228:231], v126 offset:50176
	ds_read_b128 v[232:235], v126 offset:51200
	ds_read_b128 v[236:239], v126 offset:52224
	ds_read_b128 v[160:163], v128 offset:57344
	ds_read_b128 v[164:167], v128 offset:58368
	ds_read_b128 v[168:171], v128 offset:59392
	ds_read_b128 v[122:125], v128 offset:60416
	s_waitcnt lgkmcnt(10)
	v_mfma_f32_16x16x32_bf16 v[2:5], v[240:243], v[224:227], v[2:5]
	s_waitcnt lgkmcnt(9)
	v_mfma_f32_16x16x32_bf16 v[6:9], v[244:247], v[224:227], v[6:9]
	s_waitcnt lgkmcnt(8)
	v_mfma_f32_16x16x32_bf16 v[10:13], v[248:251], v[224:227], v[10:13]
	s_waitcnt lgkmcnt(7)
	v_mfma_f32_16x16x32_bf16 v[14:17], v[156:159], v[224:227], v[14:17]
	s_waitcnt lgkmcnt(6)
	v_mfma_f32_16x16x32_bf16 v[18:21], v[240:243], v[228:231], v[18:21]
	v_mfma_f32_16x16x32_bf16 v[22:25], v[244:247], v[228:231], v[22:25]
	v_mfma_f32_16x16x32_bf16 v[26:29], v[248:251], v[228:231], v[26:29]
	v_mfma_f32_16x16x32_bf16 v[30:33], v[156:159], v[228:231], v[30:33]
	s_waitcnt lgkmcnt(5)
	v_mfma_f32_16x16x32_bf16 v[34:37], v[240:243], v[232:235], v[34:37]
	v_mfma_f32_16x16x32_bf16 v[38:41], v[244:247], v[232:235], v[38:41]
	v_mfma_f32_16x16x32_bf16 v[42:45], v[248:251], v[232:235], v[42:45]
	v_mfma_f32_16x16x32_bf16 v[46:49], v[156:159], v[232:235], v[46:49]
	s_waitcnt lgkmcnt(4)
	v_mfma_f32_16x16x32_bf16 v[50:53], v[240:243], v[236:239], v[50:53]
	v_mfma_f32_16x16x32_bf16 v[54:57], v[244:247], v[236:239], v[54:57]
	v_mfma_f32_16x16x32_bf16 v[58:61], v[248:251], v[236:239], v[58:61]
	v_mfma_f32_16x16x32_bf16 v[62:65], v[156:159], v[236:239], v[62:65]
	s_waitcnt lgkmcnt(3)
	v_mfma_f32_16x16x32_bf16 v[74:77], v[160:163], v[224:227], v[74:77]
	s_waitcnt lgkmcnt(2)
	v_mfma_f32_16x16x32_bf16 v[78:81], v[164:167], v[224:227], v[78:81]
	s_waitcnt lgkmcnt(1)
	v_mfma_f32_16x16x32_bf16 v[82:85], v[168:171], v[224:227], v[82:85]
	s_waitcnt lgkmcnt(0)
	v_mfma_f32_16x16x32_bf16 v[86:89], v[122:125], v[224:227], v[86:89]
	v_mfma_f32_16x16x32_bf16 v[90:93], v[160:163], v[228:231], v[90:93]
	v_mfma_f32_16x16x32_bf16 v[94:97], v[164:167], v[228:231], v[94:97]
	v_mfma_f32_16x16x32_bf16 v[98:101], v[168:171], v[228:231], v[98:101]
	v_mfma_f32_16x16x32_bf16 v[102:105], v[122:125], v[228:231], v[102:105]
	v_mfma_f32_16x16x32_bf16 v[106:109], v[160:163], v[232:235], v[106:109]
	v_mfma_f32_16x16x32_bf16 v[110:113], v[164:167], v[232:235], v[110:113]
	v_mfma_f32_16x16x32_bf16 v[114:117], v[168:171], v[232:235], v[114:117]
	v_mfma_f32_16x16x32_bf16 v[118:121], v[122:125], v[232:235], v[118:121]
	v_mfma_f32_16x16x32_bf16 v[208:211], v[160:163], v[236:239], v[208:211]
	v_mfma_f32_16x16x32_bf16 v[212:215], v[164:167], v[236:239], v[212:215]
	v_mfma_f32_16x16x32_bf16 v[216:219], v[168:171], v[236:239], v[216:219]
	v_mfma_f32_16x16x32_bf16 v[220:223], v[122:125], v[236:239], v[220:223]
	s_sub_u32 s46, s46, 1
	s_cmp_lg_u32 s46, 0
	s_cbranch_scc1 .Lout_kloop
	s_waitcnt vmcnt(6)
	s_barrier
	ds_read_b128 v[224:227], v126 offset:0
	ds_read_b128 v[240:243], v128 offset:0
	ds_read_b128 v[244:247], v128 offset:1024
	ds_read_b128 v[248:251], v128 offset:2048
	ds_read_b128 v[156:159], v128 offset:3072
	ds_read_b128 v[228:231], v126 offset:1024
	ds_read_b128 v[232:235], v126 offset:2048
	ds_read_b128 v[236:239], v126 offset:3072
	ds_read_b128 v[160:163], v128 offset:8192
	ds_read_b128 v[164:167], v128 offset:9216
	ds_read_b128 v[168:171], v128 offset:10240
	ds_read_b128 v[122:125], v128 offset:11264
	s_waitcnt lgkmcnt(10)
	v_mfma_f32_16x16x32_bf16 v[2:5], v[240:243], v[224:227], v[2:5]
	s_waitcnt lgkmcnt(9)
	v_mfma_f32_16x16x32_bf16 v[6:9], v[244:247], v[224:227], v[6:9]
	s_waitcnt lgkmcnt(8)
	v_mfma_f32_16x16x32_bf16 v[10:13], v[248:251], v[224:227], v[10:13]
	s_waitcnt lgkmcnt(7)
	v_mfma_f32_16x16x32_bf16 v[14:17], v[156:159], v[224:227], v[14:17]
	s_waitcnt lgkmcnt(6)
	v_mfma_f32_16x16x32_bf16 v[18:21], v[240:243], v[228:231], v[18:21]
	v_mfma_f32_16x16x32_bf16 v[22:25], v[244:247], v[228:231], v[22:25]
	v_mfma_f32_16x16x32_bf16 v[26:29], v[248:251], v[228:231], v[26:29]
	v_mfma_f32_16x16x32_bf16 v[30:33], v[156:159], v[228:231], v[30:33]
	s_waitcnt lgkmcnt(5)
	v_mfma_f32_16x16x32_bf16 v[34:37], v[240:243], v[232:235], v[34:37]
	v_mfma_f32_16x16x32_bf16 v[38:41], v[244:247], v[232:235], v[38:41]
	v_mfma_f32_16x16x32_bf16 v[42:45], v[248:251], v[232:235], v[42:45]
	v_mfma_f32_16x16x32_bf16 v[46:49], v[156:159], v[232:235], v[46:49]
	s_waitcnt lgkmcnt(4)
	v_mfma_f32_16x16x32_bf16 v[50:53], v[240:243], v[236:239], v[50:53]
	v_mfma_f32_16x16x32_bf16 v[54:57], v[244:247], v[236:239], v[54:57]
	v_mfma_f32_16x16x32_bf16 v[58:61], v[248:251], v[236:239], v[58:61]
	v_mfma_f32_16x16x32_bf16 v[62:65], v[156:159], v[236:239], v[62:65]
	s_waitcnt lgkmcnt(3)
	v_mfma_f32_16x16x32_bf16 v[74:77], v[160:163], v[224:227], v[74:77]
	s_waitcnt lgkmcnt(2)
	v_mfma_f32_16x16x32_bf16 v[78:81], v[164:167], v[224:227], v[78:81]
	s_waitcnt lgkmcnt(1)
	v_mfma_f32_16x16x32_bf16 v[82:85], v[168:171], v[224:227], v[82:85]
	s_waitcnt lgkmcnt(0)
	v_mfma_f32_16x16x32_bf16 v[86:89], v[122:125], v[224:227], v[86:89]
	v_mfma_f32_16x16x32_bf16 v[90:93], v[160:163], v[228:231], v[90:93]
	v_mfma_f32_16x16x32_bf16 v[94:97], v[164:167], v[228:231], v[94:97]
	v_mfma_f32_16x16x32_bf16 v[98:101], v[168:171], v[228:231], v[98:101]
	v_mfma_f32_16x16x32_bf16 v[102:105], v[122:125], v[228:231], v[102:105]
	v_mfma_f32_16x16x32_bf16 v[106:109], v[160:163], v[232:235], v[106:109]
	v_mfma_f32_16x16x32_bf16 v[110:113], v[164:167], v[232:235], v[110:113]
	v_mfma_f32_16x16x32_bf16 v[114:117], v[168:171], v[232:235], v[114:117]
	v_mfma_f32_16x16x32_bf16 v[118:121], v[122:125], v[232:235], v[118:121]
	v_mfma_f32_16x16x32_bf16 v[208:211], v[160:163], v[236:239], v[208:211]
	v_mfma_f32_16x16x32_bf16 v[212:215], v[164:167], v[236:239], v[212:215]
	v_mfma_f32_16x16x32_bf16 v[216:219], v[168:171], v[236:239], v[216:219]
	v_mfma_f32_16x16x32_bf16 v[220:223], v[122:125], v[236:239], v[220:223]
	s_waitcnt vmcnt(0)
	s_barrier
; #define BLOAD(A_, B_, kt) do { _Pragma("unroll") for (int i = 0; i < 4; ++i) { \
;     A_[i] = *(const u32x4*)((const char*)Ap + (aoff + (unsigned)(32 * i * lda + (kt) * 64) * 2u)); B_[i] = *(const u32x4*)((const char*)Wt + (woff + (unsigned)(32 * i * K + (kt) * 64) * 2u)); } } while (0)
; #define BLOAD(A_, B_, kt) do { _Pragma("unroll") for (int i = 0; i < 4; ++i) { \
;     A_[i] = *(const u32x4*)((const char*)Ap + (aoff + (unsigned)(32 * i * lda + (kt) * 64) * 2u)); B_[i] = *(const u32x4*)((const char*)Wt + (woff + (unsigned)(32 * i * K + (kt) * 64) * 2u)); } } while (0)
; #define BSTORE(A_, B_, buf) do { _Pragma("unroll") for (int i = 0; i < 4; ++i) { \
;     *(u32x4*)&As[(buf) * GBUF + (srow + 32 * i) * LDT + sc8] = A_[i]; \
;     *(u32x4*)&Bs[(buf) * GBUF + (srow + 32 * i) * LDT + sc8] = B_[i]; } } while (0)
; template <int NK>
; DI void gemm_run(PF& pf, const u16* __restrict__ Ap, int lda, const u16* __restrict__ Wt, f32x16 (&acc)[2][2], char* smem) {
;     ...
; #pragma unroll
;   for (int kt = 0; kt < nk; kt += 2) {
;     BCOMP(0);
;     BSTORE(pf.a1, pf.b1, 1);
;     if (kt + 3 < nk) BLOAD(pf.a1, pf.b1, kt + 3);
;     __syncthreads();
;     BCOMP(1);
;     if (kt + 2 < nk) { BSTORE(pf.a0, pf.b0, 0); if (kt + 4 < nk) BLOAD(pf.a0, pf.b0, kt + 4); }
;     __syncthreads();
;   }
; DI void tile_outproj(const Params& p, int l, const Chunk& ck, int tile, int next, PF& pf, char* smem) {
;     ...
;   const int row = tid >> 1, half = tid & 1; float ssq = 0.f;
;   u16* xb = (u16*)(p.ws + OFF_XB) + (size_t)(m0 + row) * 1024 + n0 + half * 64;
; #pragma unroll
;   for (int c8 = 0; c8 < 8; ++c8) {
;     float v[8], x[8]; cs_ld8(Cs, row, half * 64 + c8 * 8, v); unpack8(*(const u32x4*)(xb + c8 * 8), x);
	ds_read_b128 v[224:227], v126 offset:24576
	ds_read_b128 v[240:243], v128 offset:24576
	ds_read_b128 v[244:247], v128 offset:25600
	ds_read_b128 v[248:251], v128 offset:26624
	ds_read_b128 v[156:159], v128 offset:27648
	ds_read_b128 v[228:231], v126 offset:25600
	ds_read_b128 v[232:235], v126 offset:26624
	ds_read_b128 v[236:239], v126 offset:27648
	ds_read_b128 v[160:163], v128 offset:32768
	ds_read_b128 v[164:167], v128 offset:33792
	ds_read_b128 v[168:171], v128 offset:34816
	ds_read_b128 v[122:125], v128 offset:35840
	s_waitcnt lgkmcnt(10)
	v_mfma_f32_16x16x32_bf16 v[2:5], v[240:243], v[224:227], v[2:5]
	s_waitcnt lgkmcnt(9)
	v_mfma_f32_16x16x32_bf16 v[6:9], v[244:247], v[224:227], v[6:9]
	s_waitcnt lgkmcnt(8)
	v_mfma_f32_16x16x32_bf16 v[10:13], v[248:251], v[224:227], v[10:13]
	s_waitcnt lgkmcnt(7)
	v_mfma_f32_16x16x32_bf16 v[14:17], v[156:159], v[224:227], v[14:17]
	s_waitcnt lgkmcnt(6)
	v_mfma_f32_16x16x32_bf16 v[18:21], v[240:243], v[228:231], v[18:21]
	v_mfma_f32_16x16x32_bf16 v[22:25], v[244:247], v[228:231], v[22:25]
	v_mfma_f32_16x16x32_bf16 v[26:29], v[248:251], v[228:231], v[26:29]
	v_mfma_f32_16x16x32_bf16 v[30:33], v[156:159], v[228:231], v[30:33]
	s_waitcnt lgkmcnt(5)
	v_mfma_f32_16x16x32_bf16 v[34:37], v[240:243], v[232:235], v[34:37]
	v_mfma_f32_16x16x32_bf16 v[38:41], v[244:247], v[232:235], v[38:41]
	v_mfma_f32_16x16x32_bf16 v[42:45], v[248:251], v[232:235], v[42:45]
	v_mfma_f32_16x16x32_bf16 v[46:49], v[156:159], v[232:235], v[46:49]
	s_waitcnt lgkmcnt(4)
	v_mfma_f32_16x16x32_bf16 v[50:53], v[240:243], v[236:239], v[50:53]
	v_mfma_f32_16x16x32_bf16 v[54:57], v[244:247], v[236:239], v[54:57]
	v_mfma_f32_16x16x32_bf16 v[58:61], v[248:251], v[236:239], v[58:61]
	v_mfma_f32_16x16x32_bf16 v[62:65], v[156:159], v[236:239], v[62:65]
	s_waitcnt lgkmcnt(3)
	v_mfma_f32_16x16x32_bf16 v[74:77], v[160:163], v[224:227], v[74:77]
	s_waitcnt lgkmcnt(2)
	v_mfma_f32_16x16x32_bf16 v[78:81], v[164:167], v[224:227], v[78:81]
	s_waitcnt lgkmcnt(1)
	v_mfma_f32_16x16x32_bf16 v[82:85], v[168:171], v[224:227], v[82:85]
	s_waitcnt lgkmcnt(0)
	v_mfma_f32_16x16x32_bf16 v[86:89], v[122:125], v[224:227], v[86:89]
	v_mfma_f32_16x16x32_bf16 v[90:93], v[160:163], v[228:231], v[90:93]
	v_mfma_f32_16x16x32_bf16 v[94:97], v[164:167], v[228:231], v[94:97]
	v_mfma_f32_16x16x32_bf16 v[98:101], v[168:171], v[228:231], v[98:101]
	v_mfma_f32_16x16x32_bf16 v[102:105], v[122:125], v[228:231], v[102:105]
	v_mfma_f32_16x16x32_bf16 v[106:109], v[160:163], v[232:235], v[106:109]
	v_mfma_f32_16x16x32_bf16 v[110:113], v[164:167], v[232:235], v[110:113]
	v_mfma_f32_16x16x32_bf16 v[114:117], v[168:171], v[232:235], v[114:117]
	v_mfma_f32_16x16x32_bf16 v[118:121], v[122:125], v[232:235], v[118:121]
	v_mfma_f32_16x16x32_bf16 v[208:211], v[160:163], v[236:239], v[208:211]
	v_mfma_f32_16x16x32_bf16 v[212:215], v[164:167], v[236:239], v[212:215]
	v_mfma_f32_16x16x32_bf16 v[216:219], v[168:171], v[236:239], v[216:219]
	v_mfma_f32_16x16x32_bf16 v[220:223], v[122:125], v[236:239], v[220:223]
	s_barrier
	s_and_b32 s0, s40, 0x3f80
	v_and_b32_e32 v160, 63, v172
	v_lshrrev_b32_e32 v161, 6, v172
	v_and_b32_e32 v162, 15, v160
	v_lshrrev_b32_e32 v163, 4, v160
	v_lshrrev_b32_e32 v167, 1, v161
	v_lshl_add_u32 v167, v167, 6, v162
	v_and_b32_e32 v168, 1, v161
	v_lshlrev_b32_e32 v169, 6, v168
	v_lshl_add_u32 v169, v163, 2, v169
	v_add_u32_e32 v169, s26, v169
	v_add_u32_e32 v170, s0, v167
	v_lshlrev_b32_e32 v164, 11, v170
	v_lshl_add_u32 v164, v169, 1, v164
	v_lshlrev_b32_e32 v165, 12, v167
	v_lshl_add_u32 v165, v169, 2, v165
	v_lshlrev_b32_e32 v166, 6, v170
	v_lshl_add_u32 v166, v168, 2, v166
	s_lshr_b32 s0, s26, 4
	s_add_u32 s14, s22, s0
	s_addc_u32 s15, s23, 0
	global_load_dwordx2 v[224:225], v164, s[20:21] offset:0
	global_load_dwordx2 v[226:227], v164, s[20:21] offset:32
	global_load_dwordx2 v[228:229], v164, s[20:21] offset:64
	global_load_dwordx2 v[230:231], v164, s[20:21] offset:96
	v_add_u32_e32 v164, 0x8000, v164
	global_load_dwordx2 v[232:233], v164, s[20:21] offset:0
	global_load_dwordx2 v[234:235], v164, s[20:21] offset:32
	global_load_dwordx2 v[236:237], v164, s[20:21] offset:64
	global_load_dwordx2 v[238:239], v164, s[20:21] offset:96
	v_add_u32_e32 v164, 0x8000, v164
	global_load_dwordx2 v[240:241], v164, s[20:21] offset:0
	global_load_dwordx2 v[242:243], v164, s[20:21] offset:32
	global_load_dwordx2 v[244:245], v164, s[20:21] offset:64
	global_load_dwordx2 v[246:247], v164, s[20:21] offset:96
	v_add_u32_e32 v164, 0x8000, v164
	global_load_dwordx2 v[248:249], v164, s[20:21] offset:0
	global_load_dwordx2 v[250:251], v164, s[20:21] offset:32
	global_load_dwordx2 v[156:157], v164, s[20:21] offset:64
	global_load_dwordx2 v[158:159], v164, s[20:21] offset:96
	v_subrev_u32_e32 v164, 0x18000, v164
	s_waitcnt vmcnt(0)
; DI u32x4 pack8(const float (&v)[8]) { u32x4 r = {pk2(v[0], v[1]), pk2(v[2], v[3]), pk2(v[4], v[5]), pk2(v[6], v[7])}; return r; }
; DI void tile_outproj(const Params& p, int l, const Chunk& ck, int tile, int next, PF& pf, char* smem) {
;     ...
;   const int row = tid >> 1, half = tid & 1; float ssq = 0.f;
;   u16* xb = (u16*)(p.ws + OFF_XB) + (size_t)(m0 + row) * 1024 + n0 + half * 64;
; #pragma unroll
;   for (int c8 = 0; c8 < 8; ++c8) {
;     float v[8], x[8]; cs_ld8(Cs, row, half * 64 + c8 * 8, v); unpack8(*(const u32x4*)(xb + c8 * 8), x);
; #pragma unroll
;     for (int j = 0; j < 8; ++j) { v[j] += x[j]; ssq += v[j] * v[j]; }
;     *(u32x4*)(xb + c8 * 8) = pack8(v);
;   }
;   ((float*)(p.ws + OFF_PSMID))[(size_t)(m0 + row) * 16 + ni * 2 + half] = ssq;
	v_mov_b32_e32 v171, 0
	v_lshlrev_b32_e32 v167, 16, v224
	v_and_b32_e32 v168, 0xffff0000, v224
	v_lshlrev_b32_e32 v169, 16, v225
	v_and_b32_e32 v170, 0xffff0000, v225
	v_add_f32_e32 v2, v2, v167
	v_add_f32_e32 v3, v3, v168
	v_add_f32_e32 v4, v4, v169
	v_add_f32_e32 v5, v5, v170
	v_fma_f32 v171, v2, v2, v171
	v_fma_f32 v171, v3, v3, v171
	v_fma_f32 v171, v4, v4, v171
	v_fma_f32 v171, v5, v5, v171
	v_cvt_pk_bf16_f32 v2, v2, v3
	v_cvt_pk_bf16_f32 v3, v4, v5
	global_store_dwordx2 v164, v[2:3], s[20:21]
	v_lshlrev_b32_e32 v167, 16, v226
	v_and_b32_e32 v168, 0xffff0000, v226
	v_lshlrev_b32_e32 v169, 16, v227
	v_and_b32_e32 v170, 0xffff0000, v227
	v_add_f32_e32 v6, v6, v167
	v_add_f32_e32 v7, v7, v168
	v_add_f32_e32 v8, v8, v169
	v_add_f32_e32 v9, v9, v170
	v_fma_f32 v171, v6, v6, v171
	v_fma_f32 v171, v7, v7, v171
	v_fma_f32 v171, v8, v8, v171
	v_fma_f32 v171, v9, v9, v171
	v_cvt_pk_bf16_f32 v6, v6, v7
	v_cvt_pk_bf16_f32 v7, v8, v9
	global_store_dwordx2 v164, v[6:7], s[20:21] offset:32
	v_lshlrev_b32_e32 v167, 16, v228
	v_and_b32_e32 v168, 0xffff0000, v228
	v_lshlrev_b32_e32 v169, 16, v229
	v_and_b32_e32 v170, 0xffff0000, v229
	v_add_f32_e32 v10, v10, v167
	v_add_f32_e32 v11, v11, v168
	v_add_f32_e32 v12, v12, v169
	v_add_f32_e32 v13, v13, v170
	v_fma_f32 v171, v10, v10, v171
	v_fma_f32 v171, v11, v11, v171
	v_fma_f32 v171, v12, v12, v171
	v_fma_f32 v171, v13, v13, v171
	v_cvt_pk_bf16_f32 v10, v10, v11
	v_cvt_pk_bf16_f32 v11, v12, v13
	global_store_dwordx2 v164, v[10:11], s[20:21] offset:64
	v_lshlrev_b32_e32 v167, 16, v230
	v_and_b32_e32 v168, 0xffff0000, v230
	v_lshlrev_b32_e32 v169, 16, v231
	v_and_b32_e32 v170, 0xffff0000, v231
	v_add_f32_e32 v14, v14, v167
	v_add_f32_e32 v15, v15, v168
	v_add_f32_e32 v16, v16, v169
	v_add_f32_e32 v17, v17, v170
	v_fma_f32 v171, v14, v14, v171
	v_fma_f32 v171, v15, v15, v171
	v_fma_f32 v171, v16, v16, v171
	v_fma_f32 v171, v17, v17, v171
	v_cvt_pk_bf16_f32 v14, v14, v15
	v_cvt_pk_bf16_f32 v15, v16, v17
	global_store_dwordx2 v164, v[14:15], s[20:21] offset:96
	v_mov_b32_e32 v167, v171
	s_nop 1
	v_permlane32_swap_b32_e32 v171, v167
	v_add_f32_e32 v171, v171, v167
	ds_swizzle_b32 v167, v171 offset:0x401f
	s_waitcnt lgkmcnt(0)
	v_add_f32_e32 v171, v171, v167
	v_cmp_gt_u32_e32 vcc, 16, v160
	s_and_saveexec_b64 s[98:99], vcc
	global_store_dword v166, v171, s[14:15] offset:0
	s_or_b64 exec, exec, s[98:99]
	v_add_u32_e32 v164, 0x8000, v164
	v_mov_b32_e32 v171, 0
	v_lshlrev_b32_e32 v167, 16, v232
	v_and_b32_e32 v168, 0xffff0000, v232
	v_lshlrev_b32_e32 v169, 16, v233
	v_and_b32_e32 v170, 0xffff0000, v233
	v_add_f32_e32 v18, v18, v167
	v_add_f32_e32 v19, v19, v168
	v_add_f32_e32 v20, v20, v169
	v_add_f32_e32 v21, v21, v170
	v_fma_f32 v171, v18, v18, v171
	v_fma_f32 v171, v19, v19, v171
	v_fma_f32 v171, v20, v20, v171
	v_fma_f32 v171, v21, v21, v171
	v_cvt_pk_bf16_f32 v18, v18, v19
	v_cvt_pk_bf16_f32 v19, v20, v21
	global_store_dwordx2 v164, v[18:19], s[20:21]
	v_lshlrev_b32_e32 v167, 16, v234
	v_and_b32_e32 v168, 0xffff0000, v234
	v_lshlrev_b32_e32 v169, 16, v235
	v_and_b32_e32 v170, 0xffff0000, v235
	v_add_f32_e32 v22, v22, v167
	v_add_f32_e32 v23, v23, v168
	v_add_f32_e32 v24, v24, v169
	v_add_f32_e32 v25, v25, v170
	v_fma_f32 v171, v22, v22, v171
	v_fma_f32 v171, v23, v23, v171
	v_fma_f32 v171, v24, v24, v171
	v_fma_f32 v171, v25, v25, v171
	v_cvt_pk_bf16_f32 v22, v22, v23
	v_cvt_pk_bf16_f32 v23, v24, v25
	global_store_dwordx2 v164, v[22:23], s[20:21] offset:32
	v_lshlrev_b32_e32 v167, 16, v236
	v_and_b32_e32 v168, 0xffff0000, v236
	v_lshlrev_b32_e32 v169, 16, v237
	v_and_b32_e32 v170, 0xffff0000, v237
	v_add_f32_e32 v26, v26, v167
	v_add_f32_e32 v27, v27, v168
	v_add_f32_e32 v28, v28, v169
	v_add_f32_e32 v29, v29, v170
	v_fma_f32 v171, v26, v26, v171
	v_fma_f32 v171, v27, v27, v171
	v_fma_f32 v171, v28, v28, v171
	v_fma_f32 v171, v29, v29, v171
	v_cvt_pk_bf16_f32 v26, v26, v27
	v_cvt_pk_bf16_f32 v27, v28, v29
	global_store_dwordx2 v164, v[26:27], s[20:21] offset:64
	v_lshlrev_b32_e32 v167, 16, v238
	v_and_b32_e32 v168, 0xffff0000, v238
	v_lshlrev_b32_e32 v169, 16, v239
	v_and_b32_e32 v170, 0xffff0000, v239
	v_add_f32_e32 v30, v30, v167
	v_add_f32_e32 v31, v31, v168
	v_add_f32_e32 v32, v32, v169
	v_add_f32_e32 v33, v33, v170
	v_fma_f32 v171, v30, v30, v171
	v_fma_f32 v171, v31, v31, v171
	v_fma_f32 v171, v32, v32, v171
	v_fma_f32 v171, v33, v33, v171
	v_cvt_pk_bf16_f32 v30, v30, v31
	v_cvt_pk_bf16_f32 v31, v32, v33
	global_store_dwordx2 v164, v[30:31], s[20:21] offset:96
	v_mov_b32_e32 v167, v171
	s_nop 1
	v_permlane32_swap_b32_e32 v171, v167
	v_add_f32_e32 v171, v171, v167
	ds_swizzle_b32 v167, v171 offset:0x401f
	s_waitcnt lgkmcnt(0)
; DI u32x4 pack8(const float (&v)[8]) { u32x4 r = {pk2(v[0], v[1]), pk2(v[2], v[3]), pk2(v[4], v[5]), pk2(v[6], v[7])}; return r; }
; DI void tile_outproj(const Params& p, int l, const Chunk& ck, int tile, int next, PF& pf, char* smem) {
;     ...
;   const int row = tid >> 1, half = tid & 1; float ssq = 0.f;
;   u16* xb = (u16*)(p.ws + OFF_XB) + (size_t)(m0 + row) * 1024 + n0 + half * 64;
; #pragma unroll
;   for (int c8 = 0; c8 < 8; ++c8) {
;     float v[8], x[8]; cs_ld8(Cs, row, half * 64 + c8 * 8, v); unpack8(*(const u32x4*)(xb + c8 * 8), x);
; #pragma unroll
;     for (int j = 0; j < 8; ++j) { v[j] += x[j]; ssq += v[j] * v[j]; }
;     *(u32x4*)(xb + c8 * 8) = pack8(v);
;   }
;   ((float*)(p.ws + OFF_PSMID))[(size_t)(m0 + row) * 16 + ni * 2 + half] = ssq;
	v_add_f32_e32 v171, v171, v167
	v_cmp_gt_u32_e32 vcc, 16, v160
	s_and_saveexec_b64 s[98:99], vcc
	global_store_dword v166, v171, s[14:15] offset:1024
	s_or_b64 exec, exec, s[98:99]
	v_add_u32_e32 v164, 0x8000, v164
	v_mov_b32_e32 v171, 0
	v_lshlrev_b32_e32 v167, 16, v240
	v_and_b32_e32 v168, 0xffff0000, v240
	v_lshlrev_b32_e32 v169, 16, v241
	v_and_b32_e32 v170, 0xffff0000, v241
	v_add_f32_e32 v34, v34, v167
	v_add_f32_e32 v35, v35, v168
	v_add_f32_e32 v36, v36, v169
	v_add_f32_e32 v37, v37, v170
	v_fma_f32 v171, v34, v34, v171
	v_fma_f32 v171, v35, v35, v171
	v_fma_f32 v171, v36, v36, v171
	v_fma_f32 v171, v37, v37, v171
	v_cvt_pk_bf16_f32 v34, v34, v35
	v_cvt_pk_bf16_f32 v35, v36, v37
	global_store_dwordx2 v164, v[34:35], s[20:21]
	v_lshlrev_b32_e32 v167, 16, v242
	v_and_b32_e32 v168, 0xffff0000, v242
	v_lshlrev_b32_e32 v169, 16, v243
	v_and_b32_e32 v170, 0xffff0000, v243
	v_add_f32_e32 v38, v38, v167
	v_add_f32_e32 v39, v39, v168
	v_add_f32_e32 v40, v40, v169
	v_add_f32_e32 v41, v41, v170
	v_fma_f32 v171, v38, v38, v171
	v_fma_f32 v171, v39, v39, v171
	v_fma_f32 v171, v40, v40, v171
	v_fma_f32 v171, v41, v41, v171
	v_cvt_pk_bf16_f32 v38, v38, v39
	v_cvt_pk_bf16_f32 v39, v40, v41
	global_store_dwordx2 v164, v[38:39], s[20:21] offset:32
	v_lshlrev_b32_e32 v167, 16, v244
	v_and_b32_e32 v168, 0xffff0000, v244
	v_lshlrev_b32_e32 v169, 16, v245
	v_and_b32_e32 v170, 0xffff0000, v245
	v_add_f32_e32 v42, v42, v167
	v_add_f32_e32 v43, v43, v168
	v_add_f32_e32 v44, v44, v169
	v_add_f32_e32 v45, v45, v170
	v_fma_f32 v171, v42, v42, v171
	v_fma_f32 v171, v43, v43, v171
	v_fma_f32 v171, v44, v44, v171
	v_fma_f32 v171, v45, v45, v171
	v_cvt_pk_bf16_f32 v42, v42, v43
	v_cvt_pk_bf16_f32 v43, v44, v45
	global_store_dwordx2 v164, v[42:43], s[20:21] offset:64
	v_lshlrev_b32_e32 v167, 16, v246
	v_and_b32_e32 v168, 0xffff0000, v246
	v_lshlrev_b32_e32 v169, 16, v247
	v_and_b32_e32 v170, 0xffff0000, v247
	v_add_f32_e32 v46, v46, v167
	v_add_f32_e32 v47, v47, v168
	v_add_f32_e32 v48, v48, v169
	v_add_f32_e32 v49, v49, v170
	v_fma_f32 v171, v46, v46, v171
	v_fma_f32 v171, v47, v47, v171
	v_fma_f32 v171, v48, v48, v171
	v_fma_f32 v171, v49, v49, v171
	v_cvt_pk_bf16_f32 v46, v46, v47
	v_cvt_pk_bf16_f32 v47, v48, v49
	global_store_dwordx2 v164, v[46:47], s[20:21] offset:96
	v_mov_b32_e32 v167, v171
	s_nop 1
	v_permlane32_swap_b32_e32 v171, v167
	v_add_f32_e32 v171, v171, v167
	ds_swizzle_b32 v167, v171 offset:0x401f
	s_waitcnt lgkmcnt(0)
	v_add_f32_e32 v171, v171, v167
	v_cmp_gt_u32_e32 vcc, 16, v160
	s_and_saveexec_b64 s[98:99], vcc
	global_store_dword v166, v171, s[14:15] offset:2048
	s_or_b64 exec, exec, s[98:99]
	v_add_u32_e32 v164, 0x8000, v164
	v_mov_b32_e32 v171, 0
	v_lshlrev_b32_e32 v167, 16, v248
	v_and_b32_e32 v168, 0xffff0000, v248
	v_lshlrev_b32_e32 v169, 16, v249
	v_and_b32_e32 v170, 0xffff0000, v249
	v_add_f32_e32 v50, v50, v167
	v_add_f32_e32 v51, v51, v168
	v_add_f32_e32 v52, v52, v169
	v_add_f32_e32 v53, v53, v170
	v_fma_f32 v171, v50, v50, v171
	v_fma_f32 v171, v51, v51, v171
	v_fma_f32 v171, v52, v52, v171
	v_fma_f32 v171, v53, v53, v171
	v_cvt_pk_bf16_f32 v50, v50, v51
	v_cvt_pk_bf16_f32 v51, v52, v53
	global_store_dwordx2 v164, v[50:51], s[20:21]
	v_lshlrev_b32_e32 v167, 16, v250
	v_and_b32_e32 v168, 0xffff0000, v250
	v_lshlrev_b32_e32 v169, 16, v251
	v_and_b32_e32 v170, 0xffff0000, v251
	v_add_f32_e32 v54, v54, v167
	v_add_f32_e32 v55, v55, v168
	v_add_f32_e32 v56, v56, v169
	v_add_f32_e32 v57, v57, v170
	v_fma_f32 v171, v54, v54, v171
	v_fma_f32 v171, v55, v55, v171
	v_fma_f32 v171, v56, v56, v171
	v_fma_f32 v171, v57, v57, v171
	v_cvt_pk_bf16_f32 v54, v54, v55
	v_cvt_pk_bf16_f32 v55, v56, v57
	global_store_dwordx2 v164, v[54:55], s[20:21] offset:32
	v_lshlrev_b32_e32 v167, 16, v156
	v_and_b32_e32 v168, 0xffff0000, v156
	v_lshlrev_b32_e32 v169, 16, v157
	v_and_b32_e32 v170, 0xffff0000, v157
	v_add_f32_e32 v58, v58, v167
	v_add_f32_e32 v59, v59, v168
	v_add_f32_e32 v60, v60, v169
	v_add_f32_e32 v61, v61, v170
	v_fma_f32 v171, v58, v58, v171
	v_fma_f32 v171, v59, v59, v171
	v_fma_f32 v171, v60, v60, v171
	v_fma_f32 v171, v61, v61, v171
	v_cvt_pk_bf16_f32 v58, v58, v59
	v_cvt_pk_bf16_f32 v59, v60, v61
	global_store_dwordx2 v164, v[58:59], s[20:21] offset:64
	v_lshlrev_b32_e32 v167, 16, v158
	v_and_b32_e32 v168, 0xffff0000, v158
	v_lshlrev_b32_e32 v169, 16, v159
	v_and_b32_e32 v170, 0xffff0000, v159
	v_add_f32_e32 v62, v62, v167
	v_add_f32_e32 v63, v63, v168
	v_add_f32_e32 v64, v64, v169
	v_add_f32_e32 v65, v65, v170
	v_fma_f32 v171, v62, v62, v171
	v_fma_f32 v171, v63, v63, v171
	v_fma_f32 v171, v64, v64, v171
	v_fma_f32 v171, v65, v65, v171
	v_cvt_pk_bf16_f32 v62, v62, v63
	v_cvt_pk_bf16_f32 v63, v64, v65
	global_store_dwordx2 v164, v[62:63], s[20:21] offset:96
	v_mov_b32_e32 v167, v171
	s_nop 1
	v_permlane32_swap_b32_e32 v171, v167
	v_add_f32_e32 v171, v171, v167
	ds_swizzle_b32 v167, v171 offset:0x401f
	s_waitcnt lgkmcnt(0)
	v_add_f32_e32 v171, v171, v167
	v_cmp_gt_u32_e32 vcc, 16, v160
	s_and_saveexec_b64 s[98:99], vcc
	global_store_dword v166, v171, s[14:15] offset:3072
	s_or_b64 exec, exec, s[98:99]
	v_subrev_u32_e32 v164, 0x18000, v164
	global_load_dwordx2 v[224:225], v164, s[20:21] offset:256
	global_load_dwordx2 v[226:227], v164, s[20:21] offset:288
	global_load_dwordx2 v[228:229], v164, s[20:21] offset:320
	global_load_dwordx2 v[230:231], v164, s[20:21] offset:352
	v_add_u32_e32 v164, 0x8000, v164
	global_load_dwordx2 v[232:233], v164, s[20:21] offset:256
	global_load_dwordx2 v[234:235], v164, s[20:21] offset:288
	global_load_dwordx2 v[236:237], v164, s[20:21] offset:320
	global_load_dwordx2 v[238:239], v164, s[20:21] offset:352
	v_add_u32_e32 v164, 0x8000, v164
	global_load_dwordx2 v[240:241], v164, s[20:21] offset:256
	global_load_dwordx2 v[242:243], v164, s[20:21] offset:288
	global_load_dwordx2 v[244:245], v164, s[20:21] offset:320
	global_load_dwordx2 v[246:247], v164, s[20:21] offset:352
	v_add_u32_e32 v164, 0x8000, v164
	global_load_dwordx2 v[248:249], v164, s[20:21] offset:256
	global_load_dwordx2 v[250:251], v164, s[20:21] offset:288
	global_load_dwordx2 v[156:157], v164, s[20:21] offset:320
	global_load_dwordx2 v[158:159], v164, s[20:21] offset:352
	v_subrev_u32_e32 v164, 0x18000, v164
	s_waitcnt vmcnt(0)
; DI u32x4 pack8(const float (&v)[8]) { u32x4 r = {pk2(v[0], v[1]), pk2(v[2], v[3]), pk2(v[4], v[5]), pk2(v[6], v[7])}; return r; }
; DI void tile_outproj(const Params& p, int l, const Chunk& ck, int tile, int next, PF& pf, char* smem) {
;     ...
;   const int row = tid >> 1, half = tid & 1; float ssq = 0.f;
;   u16* xb = (u16*)(p.ws + OFF_XB) + (size_t)(m0 + row) * 1024 + n0 + half * 64;
; #pragma unroll
;   for (int c8 = 0; c8 < 8; ++c8) {
;     float v[8], x[8]; cs_ld8(Cs, row, half * 64 + c8 * 8, v); unpack8(*(const u32x4*)(xb + c8 * 8), x);
; #pragma unroll
;     for (int j = 0; j < 8; ++j) { v[j] += x[j]; ssq += v[j] * v[j]; }
;     *(u32x4*)(xb + c8 * 8) = pack8(v);
;   }
;   ((float*)(p.ws + OFF_PSMID))[(size_t)(m0 + row) * 16 + ni * 2 + half] = ssq;
	v_mov_b32_e32 v171, 0
	v_lshlrev_b32_e32 v167, 16, v224
	v_and_b32_e32 v168, 0xffff0000, v224
	v_lshlrev_b32_e32 v169, 16, v225
	v_and_b32_e32 v170, 0xffff0000, v225
	v_add_f32_e32 v74, v74, v167
	v_add_f32_e32 v75, v75, v168
	v_add_f32_e32 v76, v76, v169
	v_add_f32_e32 v77, v77, v170
	v_fma_f32 v171, v74, v74, v171
	v_fma_f32 v171, v75, v75, v171
	v_fma_f32 v171, v76, v76, v171
	v_fma_f32 v171, v77, v77, v171
	v_cvt_pk_bf16_f32 v74, v74, v75
	v_cvt_pk_bf16_f32 v75, v76, v77
	global_store_dwordx2 v164, v[74:75], s[20:21] offset:256
	v_lshlrev_b32_e32 v167, 16, v226
	v_and_b32_e32 v168, 0xffff0000, v226
	v_lshlrev_b32_e32 v169, 16, v227
	v_and_b32_e32 v170, 0xffff0000, v227
	v_add_f32_e32 v78, v78, v167
	v_add_f32_e32 v79, v79, v168
	v_add_f32_e32 v80, v80, v169
	v_add_f32_e32 v81, v81, v170
	v_fma_f32 v171, v78, v78, v171
	v_fma_f32 v171, v79, v79, v171
	v_fma_f32 v171, v80, v80, v171
	v_fma_f32 v171, v81, v81, v171
	v_cvt_pk_bf16_f32 v78, v78, v79
	v_cvt_pk_bf16_f32 v79, v80, v81
	global_store_dwordx2 v164, v[78:79], s[20:21] offset:288
	v_lshlrev_b32_e32 v167, 16, v228
	v_and_b32_e32 v168, 0xffff0000, v228
	v_lshlrev_b32_e32 v169, 16, v229
	v_and_b32_e32 v170, 0xffff0000, v229
	v_add_f32_e32 v82, v82, v167
	v_add_f32_e32 v83, v83, v168
	v_add_f32_e32 v84, v84, v169
	v_add_f32_e32 v85, v85, v170
	v_fma_f32 v171, v82, v82, v171
	v_fma_f32 v171, v83, v83, v171
	v_fma_f32 v171, v84, v84, v171
	v_fma_f32 v171, v85, v85, v171
	v_cvt_pk_bf16_f32 v82, v82, v83
	v_cvt_pk_bf16_f32 v83, v84, v85
	global_store_dwordx2 v164, v[82:83], s[20:21] offset:320
	v_lshlrev_b32_e32 v167, 16, v230
	v_and_b32_e32 v168, 0xffff0000, v230
	v_lshlrev_b32_e32 v169, 16, v231
	v_and_b32_e32 v170, 0xffff0000, v231
	v_add_f32_e32 v86, v86, v167
	v_add_f32_e32 v87, v87, v168
	v_add_f32_e32 v88, v88, v169
	v_add_f32_e32 v89, v89, v170
	v_fma_f32 v171, v86, v86, v171
	v_fma_f32 v171, v87, v87, v171
	v_fma_f32 v171, v88, v88, v171
	v_fma_f32 v171, v89, v89, v171
	v_cvt_pk_bf16_f32 v86, v86, v87
	v_cvt_pk_bf16_f32 v87, v88, v89
	global_store_dwordx2 v164, v[86:87], s[20:21] offset:352
	v_mov_b32_e32 v167, v171
	s_nop 1
	v_permlane32_swap_b32_e32 v171, v167
	v_add_f32_e32 v171, v171, v167
	ds_swizzle_b32 v167, v171 offset:0x401f
	s_waitcnt lgkmcnt(0)
	v_add_f32_e32 v171, v171, v167
	v_cmp_gt_u32_e32 vcc, 16, v160
	s_and_saveexec_b64 s[98:99], vcc
	global_store_dword v166, v171, s[14:15] offset:8
	s_or_b64 exec, exec, s[98:99]
	v_add_u32_e32 v164, 0x8000, v164
	v_mov_b32_e32 v171, 0
	v_lshlrev_b32_e32 v167, 16, v232
	v_and_b32_e32 v168, 0xffff0000, v232
	v_lshlrev_b32_e32 v169, 16, v233
	v_and_b32_e32 v170, 0xffff0000, v233
	v_add_f32_e32 v90, v90, v167
	v_add_f32_e32 v91, v91, v168
	v_add_f32_e32 v92, v92, v169
	v_add_f32_e32 v93, v93, v170
	v_fma_f32 v171, v90, v90, v171
	v_fma_f32 v171, v91, v91, v171
	v_fma_f32 v171, v92, v92, v171
	v_fma_f32 v171, v93, v93, v171
	v_cvt_pk_bf16_f32 v90, v90, v91
	v_cvt_pk_bf16_f32 v91, v92, v93
	global_store_dwordx2 v164, v[90:91], s[20:21] offset:256
	v_lshlrev_b32_e32 v167, 16, v234
	v_and_b32_e32 v168, 0xffff0000, v234
	v_lshlrev_b32_e32 v169, 16, v235
	v_and_b32_e32 v170, 0xffff0000, v235
	v_add_f32_e32 v94, v94, v167
	v_add_f32_e32 v95, v95, v168
	v_add_f32_e32 v96, v96, v169
	v_add_f32_e32 v97, v97, v170
	v_fma_f32 v171, v94, v94, v171
	v_fma_f32 v171, v95, v95, v171
	v_fma_f32 v171, v96, v96, v171
	v_fma_f32 v171, v97, v97, v171
	v_cvt_pk_bf16_f32 v94, v94, v95
	v_cvt_pk_bf16_f32 v95, v96, v97
	global_store_dwordx2 v164, v[94:95], s[20:21] offset:288
	v_lshlrev_b32_e32 v167, 16, v236
	v_and_b32_e32 v168, 0xffff0000, v236
	v_lshlrev_b32_e32 v169, 16, v237
	v_and_b32_e32 v170, 0xffff0000, v237
	v_add_f32_e32 v98, v98, v167
	v_add_f32_e32 v99, v99, v168
	v_add_f32_e32 v100, v100, v169
	v_add_f32_e32 v101, v101, v170
	v_fma_f32 v171, v98, v98, v171
	v_fma_f32 v171, v99, v99, v171
	v_fma_f32 v171, v100, v100, v171
	v_fma_f32 v171, v101, v101, v171
	v_cvt_pk_bf16_f32 v98, v98, v99
	v_cvt_pk_bf16_f32 v99, v100, v101
	global_store_dwordx2 v164, v[98:99], s[20:21] offset:320
	v_lshlrev_b32_e32 v167, 16, v238
	v_and_b32_e32 v168, 0xffff0000, v238
	v_lshlrev_b32_e32 v169, 16, v239
	v_and_b32_e32 v170, 0xffff0000, v239
	v_add_f32_e32 v102, v102, v167
	v_add_f32_e32 v103, v103, v168
	v_add_f32_e32 v104, v104, v169
	v_add_f32_e32 v105, v105, v170
	v_fma_f32 v171, v102, v102, v171
	v_fma_f32 v171, v103, v103, v171
	v_fma_f32 v171, v104, v104, v171
	v_fma_f32 v171, v105, v105, v171
	v_cvt_pk_bf16_f32 v102, v102, v103
	v_cvt_pk_bf16_f32 v103, v104, v105
	global_store_dwordx2 v164, v[102:103], s[20:21] offset:352
	v_mov_b32_e32 v167, v171
	s_nop 1
	v_permlane32_swap_b32_e32 v171, v167
	v_add_f32_e32 v171, v171, v167
	ds_swizzle_b32 v167, v171 offset:0x401f
	s_waitcnt lgkmcnt(0)
; DI u32x4 pack8(const float (&v)[8]) { u32x4 r = {pk2(v[0], v[1]), pk2(v[2], v[3]), pk2(v[4], v[5]), pk2(v[6], v[7])}; return r; }
; DI void tile_outproj(const Params& p, int l, const Chunk& ck, int tile, int next, PF& pf, char* smem) {
;     ...
;   const int row = tid >> 1, half = tid & 1; float ssq = 0.f;
;   u16* xb = (u16*)(p.ws + OFF_XB) + (size_t)(m0 + row) * 1024 + n0 + half * 64;
; #pragma unroll
;   for (int c8 = 0; c8 < 8; ++c8) {
;     float v[8], x[8]; cs_ld8(Cs, row, half * 64 + c8 * 8, v); unpack8(*(const u32x4*)(xb + c8 * 8), x);
; #pragma unroll
;     for (int j = 0; j < 8; ++j) { v[j] += x[j]; ssq += v[j] * v[j]; }
;     *(u32x4*)(xb + c8 * 8) = pack8(v);
;   }
;   ((float*)(p.ws + OFF_PSMID))[(size_t)(m0 + row) * 16 + ni * 2 + half] = ssq;
	v_add_f32_e32 v171, v171, v167
	v_cmp_gt_u32_e32 vcc, 16, v160
	s_and_saveexec_b64 s[98:99], vcc
	global_store_dword v166, v171, s[14:15] offset:1032
	s_or_b64 exec, exec, s[98:99]
	v_add_u32_e32 v164, 0x8000, v164
	v_mov_b32_e32 v171, 0
	v_lshlrev_b32_e32 v167, 16, v240
	v_and_b32_e32 v168, 0xffff0000, v240
	v_lshlrev_b32_e32 v169, 16, v241
	v_and_b32_e32 v170, 0xffff0000, v241
	v_add_f32_e32 v106, v106, v167
	v_add_f32_e32 v107, v107, v168
	v_add_f32_e32 v108, v108, v169
	v_add_f32_e32 v109, v109, v170
	v_fma_f32 v171, v106, v106, v171
	v_fma_f32 v171, v107, v107, v171
	v_fma_f32 v171, v108, v108, v171
	v_fma_f32 v171, v109, v109, v171
	v_cvt_pk_bf16_f32 v106, v106, v107
	v_cvt_pk_bf16_f32 v107, v108, v109
	global_store_dwordx2 v164, v[106:107], s[20:21] offset:256
	v_lshlrev_b32_e32 v167, 16, v242
	v_and_b32_e32 v168, 0xffff0000, v242
	v_lshlrev_b32_e32 v169, 16, v243
	v_and_b32_e32 v170, 0xffff0000, v243
	v_add_f32_e32 v110, v110, v167
	v_add_f32_e32 v111, v111, v168
	v_add_f32_e32 v112, v112, v169
	v_add_f32_e32 v113, v113, v170
	v_fma_f32 v171, v110, v110, v171
	v_fma_f32 v171, v111, v111, v171
	v_fma_f32 v171, v112, v112, v171
	v_fma_f32 v171, v113, v113, v171
	v_cvt_pk_bf16_f32 v110, v110, v111
	v_cvt_pk_bf16_f32 v111, v112, v113
	global_store_dwordx2 v164, v[110:111], s[20:21] offset:288
	v_lshlrev_b32_e32 v167, 16, v244
	v_and_b32_e32 v168, 0xffff0000, v244
	v_lshlrev_b32_e32 v169, 16, v245
	v_and_b32_e32 v170, 0xffff0000, v245
	v_add_f32_e32 v114, v114, v167
	v_add_f32_e32 v115, v115, v168
	v_add_f32_e32 v116, v116, v169
	v_add_f32_e32 v117, v117, v170
	v_fma_f32 v171, v114, v114, v171
	v_fma_f32 v171, v115, v115, v171
	v_fma_f32 v171, v116, v116, v171
	v_fma_f32 v171, v117, v117, v171
	v_cvt_pk_bf16_f32 v114, v114, v115
	v_cvt_pk_bf16_f32 v115, v116, v117
	global_store_dwordx2 v164, v[114:115], s[20:21] offset:320
	v_lshlrev_b32_e32 v167, 16, v246
	v_and_b32_e32 v168, 0xffff0000, v246
	v_lshlrev_b32_e32 v169, 16, v247
	v_and_b32_e32 v170, 0xffff0000, v247
	v_add_f32_e32 v118, v118, v167
	v_add_f32_e32 v119, v119, v168
	v_add_f32_e32 v120, v120, v169
	v_add_f32_e32 v121, v121, v170
	v_fma_f32 v171, v118, v118, v171
	v_fma_f32 v171, v119, v119, v171
	v_fma_f32 v171, v120, v120, v171
	v_fma_f32 v171, v121, v121, v171
	v_cvt_pk_bf16_f32 v118, v118, v119
	v_cvt_pk_bf16_f32 v119, v120, v121
	global_store_dwordx2 v164, v[118:119], s[20:21] offset:352
	v_mov_b32_e32 v167, v171
	s_nop 1
	v_permlane32_swap_b32_e32 v171, v167
	v_add_f32_e32 v171, v171, v167
	ds_swizzle_b32 v167, v171 offset:0x401f
	s_waitcnt lgkmcnt(0)
	v_add_f32_e32 v171, v171, v167
	v_cmp_gt_u32_e32 vcc, 16, v160
	s_and_saveexec_b64 s[98:99], vcc
	global_store_dword v166, v171, s[14:15] offset:2056
	s_or_b64 exec, exec, s[98:99]
	v_add_u32_e32 v164, 0x8000, v164
	v_mov_b32_e32 v171, 0
	v_lshlrev_b32_e32 v167, 16, v248
	v_and_b32_e32 v168, 0xffff0000, v248
	v_lshlrev_b32_e32 v169, 16, v249
	v_and_b32_e32 v170, 0xffff0000, v249
	v_add_f32_e32 v208, v208, v167
	v_add_f32_e32 v209, v209, v168
	v_add_f32_e32 v210, v210, v169
	v_add_f32_e32 v211, v211, v170
	v_fma_f32 v171, v208, v208, v171
	v_fma_f32 v171, v209, v209, v171
	v_fma_f32 v171, v210, v210, v171
	v_fma_f32 v171, v211, v211, v171
	v_cvt_pk_bf16_f32 v208, v208, v209
	v_cvt_pk_bf16_f32 v209, v210, v211
	global_store_dwordx2 v164, v[208:209], s[20:21] offset:256
	v_lshlrev_b32_e32 v167, 16, v250
	v_and_b32_e32 v168, 0xffff0000, v250
	v_lshlrev_b32_e32 v169, 16, v251
	v_and_b32_e32 v170, 0xffff0000, v251
	v_add_f32_e32 v212, v212, v167
	v_add_f32_e32 v213, v213, v168
	v_add_f32_e32 v214, v214, v169
	v_add_f32_e32 v215, v215, v170
	v_fma_f32 v171, v212, v212, v171
	v_fma_f32 v171, v213, v213, v171
	v_fma_f32 v171, v214, v214, v171
	v_fma_f32 v171, v215, v215, v171
	v_cvt_pk_bf16_f32 v212, v212, v213
	v_cvt_pk_bf16_f32 v213, v214, v215
	global_store_dwordx2 v164, v[212:213], s[20:21] offset:288
	v_lshlrev_b32_e32 v167, 16, v156
	v_and_b32_e32 v168, 0xffff0000, v156
	v_lshlrev_b32_e32 v169, 16, v157
	v_and_b32_e32 v170, 0xffff0000, v157
	v_add_f32_e32 v216, v216, v167
	v_add_f32_e32 v217, v217, v168
	v_add_f32_e32 v218, v218, v169
	v_add_f32_e32 v219, v219, v170
	v_fma_f32 v171, v216, v216, v171
	v_fma_f32 v171, v217, v217, v171
	v_fma_f32 v171, v218, v218, v171
	v_fma_f32 v171, v219, v219, v171
	v_cvt_pk_bf16_f32 v216, v216, v217
	v_cvt_pk_bf16_f32 v217, v218, v219
	global_store_dwordx2 v164, v[216:217], s[20:21] offset:320
	v_lshlrev_b32_e32 v167, 16, v158
	v_and_b32_e32 v168, 0xffff0000, v158
	v_lshlrev_b32_e32 v169, 16, v159
	v_and_b32_e32 v170, 0xffff0000, v159
	v_add_f32_e32 v220, v220, v167
	v_add_f32_e32 v221, v221, v168
	v_add_f32_e32 v222, v222, v169
	v_add_f32_e32 v223, v223, v170
	v_fma_f32 v171, v220, v220, v171
	v_fma_f32 v171, v221, v221, v171
	v_fma_f32 v171, v222, v222, v171
	v_fma_f32 v171, v223, v223, v171
	v_cvt_pk_bf16_f32 v220, v220, v221
	v_cvt_pk_bf16_f32 v221, v222, v223
	global_store_dwordx2 v164, v[220:221], s[20:21] offset:352
	v_mov_b32_e32 v167, v171
	s_nop 1
	v_permlane32_swap_b32_e32 v171, v167
	v_add_f32_e32 v171, v171, v167
	ds_swizzle_b32 v167, v171 offset:0x401f
	s_waitcnt lgkmcnt(0)
	v_add_f32_e32 v171, v171, v167
	v_cmp_gt_u32_e32 vcc, 16, v160
	s_and_saveexec_b64 s[98:99], vcc
	global_store_dword v166, v171, s[14:15] offset:3080
	s_or_b64 exec, exec, s[98:99]
	v_subrev_u32_e32 v164, 0x18000, v164
	s_branch .LBB1_254

; DI int TID() { int t = (int)__builtin_amdgcn_workitem_id_x(); asm volatile("" : "+v"(t)); return t; }
; DI void st8(u16* dst, const float (&v)[8]) { *(u32x4*)dst = pack8(v); }
; DI RowSS rowss_load(const float* ps, int m0) { const int tid = TID(); const float* q = ps + (size_t)(m0 + (tid >> 1)) * 16 + (tid & 1) * 8; RowSS r; r.a = *(const f32x4*)q; r.b = *(const f32x4*)(q + 4); return r; }
; DI void tile_branch(const Params& p, int l, int tile, char* smem) {
;   float* Cs = (float*)smem;
;   const int tid = TID(), lane = tid & 63, w = tid >> 6, wm = w >> 1, wn = w & 1, r32 = lane & 31, hi = lane >> 5;
;   const int mi = tile & (MTN - 1), ni = tile >> MTS; const int m0 = mi * 128, n0 = ni * 128;
;   unsigned upk[2][2][8];
; #pragma unroll
;   for (int a = 0; a < 2; ++a)
; #pragma unroll
;     for (int b = 0; b < 2; ++b)
; #pragma unroll
;       for (int i = 0; i < 8; ++i) upk[a][b][i] = 0u;
;   float* rinv_s = (float*)(smem + SMEM_CS);
;   { const RowSS rss = rowss_load((const float*)(p.ws + OFF_PSIN), m0); rowss_finish(rss, rinv_s); }
; #pragma unroll 1
;   for (int br = 0; br < 3; ++br) {
;     unsigned gpk[2][2][8];
;     {
;       f32x16 accg[2][2]; zero_acc(accg);
;       gemm_main_bf<false, 16>((const u16*)(p.ws + OFF_XB) + (size_t)m0 * 1024, 1024,
;                               (const u16*)(p.ws + OFF_WIN + l * SZ_WIN) + (size_t)(5760 + br * 1024 + n0) * 1024, accg, smem, nullptr);
;     ...
;   const int row = tid >> 1, half = tid & 1; float v[8];
;   u16* dst = (u16*)(p.ws + OFF_U) + (size_t)(m0 + row) * 1024 + n0 + half * 64;
; #pragma unroll
;   for (int c8 = 0; c8 < 8; ++c8) { cs_ld8(Cs, row, half * 64 + c8 * 8, v); st8(dst + c8 * 8, v); }
.LBB1_264:
	s_or_b64 exec, exec, s[26:27]
	v_and_b32_e32 v246, 63, v172
	v_lshrrev_b32_e32 v247, 6, v172
	v_bfe_u32 v166, v246, 4, 2
	v_lshrrev_b32_e32 v167, 1, v166
	v_xor_b32_e32 v166, v166, v167
	v_and_b32_e32 v166, 1, v166
	v_lshl_or_b32 v166, v166, 1, v167
	v_xor_b32_e32 v166, v166, v246
	v_and_b32_e32 v166, 3, v166
	v_lshlrev_b32_e32 v166, 4, v166
	v_lshrrev_b32_e32 v167, 2, v246
	v_lshl_add_u32 v168, v247, 5, v167
	v_lshl_add_u32 v242, v168, 11, v166
	v_add_u32_e32 v243, 0x7c00, v242
	v_lshl_add_u32 v244, v168, 10, v166
	v_add_u32_e32 v245, 0x3c00, v244
	v_lshl_add_u32 v251, v168, 6, v166
	v_readfirstlane_b32 s52, v247
	s_lshl_b32 s52, s52, 11
	s_add_u32 s53, s52, 0x2000
	v_bfe_u32 v166, v246, 2, 2
	v_lshrrev_b32_e32 v167, 1, v166
	v_xor_b32_e32 v166, v166, v167
	v_and_b32_e32 v166, 1, v166
	v_lshl_or_b32 v166, v166, 1, v167
	v_lshrrev_b32_e32 v171, 4, v246
	v_xor_b32_e32 v166, v166, v171
	v_lshlrev_b32_e32 v166, 4, v166
	v_and_b32_e32 v169, 15, v246
	v_lshl_add_u32 v170, v169, 6, v166
	v_lshrrev_b32_e32 v166, 1, v247
	v_and_b32_e32 v167, 1, v247
	v_lshl_add_u32 v240, v166, 12, v170
	v_lshl_add_u32 v241, v167, 12, v170
	v_add_u32_e32 v241, 0x2000, v241
	v_lshl_add_u32 v248, v166, 6, v169
	v_lshlrev_b32_e32 v250, 2, v248
	v_add_u32_e32 v250, 0x12000, v250
	v_lshlrev_b32_e32 v167, 6, v167
	v_lshl_add_u32 v167, v171, 2, v167
	s_and_b32 s12, s17, 0xffffff80
	v_add_u32_e32 v167, s12, v167
	v_add_u32_e32 v168, s16, v248
	v_lshlrev_b32_e32 v249, 6, v168
	v_lshl_add_u32 v249, v171, 3, v249
	v_lshrrev_b32_e32 v167, 5, v167
	v_lshl_add_u32 v249, v167, 20, v249
	s_lshl_b32 s0, s16, 11
	s_add_u32 s44, s34, s0
	s_addc_u32 s45, s35, 0
	s_lshl_b32 s0, s12, 6
	s_add_u32 s0, s0, 0xb40000
	s_add_u32 s46, s93, s0
	s_addc_u32 s47, s42, 0
	s_lshl_b32 s0, s16, 10
	s_add_u32 s48, s18, s96
	s_addc_u32 s49, s19, 0
	s_add_u32 s48, s48, s0
	s_addc_u32 s49, s49, 0
	s_add_u32 s50, s18, s97
	s_addc_u32 s51, s19, 0
	s_add_u32 s50, s50, s24
	s_addc_u32 s51, s51, s25
	s_lshl_b32 s0, s12, 6
	s_add_u32 s50, s50, s0
	s_addc_u32 s51, s51, 0
	s_mov_b64 s[28:29], s[44:45]
	s_mov_b64 s[30:31], s[46:47]
	s_add_u32 m0, s52, 0x0
	s_nop 0
	global_load_lds_dwordx4 v242, s[28:29]
	global_load_lds_dwordx4 v243, s[28:29] offset:1024
	s_add_u32 m0, s53, 0x0
	s_nop 0
	global_load_lds_dwordx4 v251, s[30:31]
	global_load_lds_dwordx4 v251, s[30:31] offset:1024
	s_add_u32 m0, s52, 0x4000
	s_add_u32 s28, s28, 0x40
	s_addc_u32 s29, s29, 0
	global_load_lds_dwordx4 v242, s[28:29]
	global_load_lds_dwordx4 v243, s[28:29] offset:1024
	s_add_u32 m0, s53, 0x4000
	s_add_u32 s30, s30, 0x30000
	s_addc_u32 s31, s31, 0
	global_load_lds_dwordx4 v251, s[30:31]
	global_load_lds_dwordx4 v251, s[30:31] offset:1024
	s_add_u32 m0, s52, 0x8000
	s_add_u32 s28, s28, 0x40
	s_addc_u32 s29, s29, 0
	global_load_lds_dwordx4 v242, s[28:29]
	global_load_lds_dwordx4 v243, s[28:29] offset:1024
	s_add_u32 m0, s53, 0x8000
	s_add_u32 s30, s30, 0x30000
	s_addc_u32 s31, s31, 0
	global_load_lds_dwordx4 v251, s[30:31]
	global_load_lds_dwordx4 v251, s[30:31] offset:1024
	v_mov_b32_e32 v66, 0
	v_mov_b32_e32 v67, 0
	v_mov_b32_e32 v68, 0
	v_mov_b32_e32 v69, 0
	v_mov_b32_e32 v70, 0
	v_mov_b32_e32 v71, 0
	v_mov_b32_e32 v72, 0
	v_mov_b32_e32 v73, 0
	v_mov_b32_e32 v74, 0
	v_mov_b32_e32 v75, 0
	v_mov_b32_e32 v76, 0
	v_mov_b32_e32 v77, 0
	v_mov_b32_e32 v78, 0
	v_mov_b32_e32 v79, 0
	v_mov_b32_e32 v80, 0
	v_mov_b32_e32 v81, 0
	v_mov_b32_e32 v82, 0
	v_mov_b32_e32 v83, 0
	v_mov_b32_e32 v84, 0
	v_mov_b32_e32 v85, 0
	v_mov_b32_e32 v86, 0
	v_mov_b32_e32 v87, 0
	v_mov_b32_e32 v88, 0
	v_mov_b32_e32 v89, 0
	v_mov_b32_e32 v90, 0
	v_mov_b32_e32 v91, 0
	v_mov_b32_e32 v92, 0
	v_mov_b32_e32 v93, 0
	v_mov_b32_e32 v94, 0
	v_mov_b32_e32 v95, 0
	v_mov_b32_e32 v96, 0
	v_mov_b32_e32 v97, 0
	v_mov_b32_e32 v98, 0
	v_mov_b32_e32 v99, 0
	v_mov_b32_e32 v100, 0
	v_mov_b32_e32 v101, 0
	v_mov_b32_e32 v102, 0
	v_mov_b32_e32 v103, 0
	v_mov_b32_e32 v104, 0
	v_mov_b32_e32 v105, 0
	v_mov_b32_e32 v106, 0
	v_mov_b32_e32 v107, 0
	v_mov_b32_e32 v108, 0
	v_mov_b32_e32 v109, 0
	v_mov_b32_e32 v110, 0
	v_mov_b32_e32 v111, 0
	v_mov_b32_e32 v112, 0
	v_mov_b32_e32 v113, 0
	v_mov_b32_e32 v114, 0
	v_mov_b32_e32 v115, 0
	v_mov_b32_e32 v116, 0
	v_mov_b32_e32 v117, 0
	v_mov_b32_e32 v118, 0
	v_mov_b32_e32 v119, 0
	v_mov_b32_e32 v120, 0
	v_mov_b32_e32 v121, 0
	v_mov_b32_e32 v122, 0
	v_mov_b32_e32 v123, 0
	v_mov_b32_e32 v124, 0
	v_mov_b32_e32 v125, 0
	v_mov_b32_e32 v126, 0
	v_mov_b32_e32 v127, 0
	v_mov_b32_e32 v128, 0
	v_mov_b32_e32 v129, 0
	s_mov_b32 s75, 0

; DI unsigned pk2(float a, float b) { f2_t v = {a, b}; bf2_t r = __builtin_convertvector(v, bf2_t); return __builtin_bit_cast(unsigned, r); }
; DI void st8(u16* dst, const float (&v)[8]) { *(u32x4*)dst = pack8(v); }
; DI void tile_branch(const Params& p, int l, int tile, char* smem) {
;     ...
; #pragma unroll
;     for (int mt = 0; mt < 2; ++mt)
; #pragma unroll
;       for (int nt = 0; nt < 2; ++nt)
; #pragma unroll
;         for (int i = 0; i < 8; ++i) {
;           const float g0 = __uint_as_float(gpk[mt][nt][i] << 16), g1 = __uint_as_float(gpk[mt][nt][i] & 0xffff0000u);
;           const float a = __uint_as_float(upk[mt][nt][i] << 16) + g0 * acc[mt][nt][2 * i];
;           const float b = __uint_as_float(upk[mt][nt][i] & 0xffff0000u) + g1 * acc[mt][nt][2 * i + 1];
;           upk[mt][nt][i] = pk2(a, b);
;         }
;     ...
;   const int row = tid >> 1, half = tid & 1; float v[8];
;   u16* dst = (u16*)(p.ws + OFF_U) + (size_t)(m0 + row) * 1024 + n0 + half * 64;
; #pragma unroll
;   for (int c8 = 0; c8 < 8; ++c8) { cs_ld8(Cs, row, half * 64 + c8 * 8, v); st8(dst + c8 * 8, v); }
.Lbr_noprol:
	v_lshlrev_b32_e32 v166, 16, v130
	v_and_b32_e32 v167, 0xffff0000, v130
	v_lshlrev_b32_e32 v168, 16, v131
	v_and_b32_e32 v169, 0xffff0000, v131
	v_fmac_f32_e32 v66, v166, v2
	v_fmac_f32_e32 v67, v167, v3
	v_fmac_f32_e32 v68, v168, v4
	v_fmac_f32_e32 v69, v169, v5
	v_lshlrev_b32_e32 v166, 16, v132
	v_and_b32_e32 v167, 0xffff0000, v132
	v_lshlrev_b32_e32 v168, 16, v133
	v_and_b32_e32 v169, 0xffff0000, v133
	v_fmac_f32_e32 v70, v166, v6
	v_fmac_f32_e32 v71, v167, v7
	v_fmac_f32_e32 v72, v168, v8
	v_fmac_f32_e32 v73, v169, v9
	v_lshlrev_b32_e32 v166, 16, v134
	v_and_b32_e32 v167, 0xffff0000, v134
	v_lshlrev_b32_e32 v168, 16, v135
	v_and_b32_e32 v169, 0xffff0000, v135
	v_fmac_f32_e32 v74, v166, v10
	v_fmac_f32_e32 v75, v167, v11
	v_fmac_f32_e32 v76, v168, v12
	v_fmac_f32_e32 v77, v169, v13
	v_lshlrev_b32_e32 v166, 16, v136
	v_and_b32_e32 v167, 0xffff0000, v136
	v_lshlrev_b32_e32 v168, 16, v137
	v_and_b32_e32 v169, 0xffff0000, v137
	v_fmac_f32_e32 v78, v166, v14
	v_fmac_f32_e32 v79, v167, v15
	v_fmac_f32_e32 v80, v168, v16
	v_fmac_f32_e32 v81, v169, v17
	v_lshlrev_b32_e32 v166, 16, v138
	v_and_b32_e32 v167, 0xffff0000, v138
	v_lshlrev_b32_e32 v168, 16, v139
	v_and_b32_e32 v169, 0xffff0000, v139
	v_fmac_f32_e32 v82, v166, v18
	v_fmac_f32_e32 v83, v167, v19
	v_fmac_f32_e32 v84, v168, v20
	v_fmac_f32_e32 v85, v169, v21
	v_lshlrev_b32_e32 v166, 16, v140
	v_and_b32_e32 v167, 0xffff0000, v140
	v_lshlrev_b32_e32 v168, 16, v141
	v_and_b32_e32 v169, 0xffff0000, v141
	v_fmac_f32_e32 v86, v166, v22
	v_fmac_f32_e32 v87, v167, v23
	v_fmac_f32_e32 v88, v168, v24
	v_fmac_f32_e32 v89, v169, v25
	v_lshlrev_b32_e32 v166, 16, v142
	v_and_b32_e32 v167, 0xffff0000, v142
	v_lshlrev_b32_e32 v168, 16, v143
	v_and_b32_e32 v169, 0xffff0000, v143
	v_fmac_f32_e32 v90, v166, v26
	v_fmac_f32_e32 v91, v167, v27
	v_fmac_f32_e32 v92, v168, v28
	v_fmac_f32_e32 v93, v169, v29
	v_lshlrev_b32_e32 v166, 16, v144
	v_and_b32_e32 v167, 0xffff0000, v144
	v_lshlrev_b32_e32 v168, 16, v145
	v_and_b32_e32 v169, 0xffff0000, v145
	v_fmac_f32_e32 v94, v166, v30
	v_fmac_f32_e32 v95, v167, v31
	v_fmac_f32_e32 v96, v168, v32
	v_fmac_f32_e32 v97, v169, v33
	v_lshlrev_b32_e32 v166, 16, v146
	v_and_b32_e32 v167, 0xffff0000, v146
	v_lshlrev_b32_e32 v168, 16, v147
	v_and_b32_e32 v169, 0xffff0000, v147
	v_fmac_f32_e32 v98, v166, v34
	v_fmac_f32_e32 v99, v167, v35
	v_fmac_f32_e32 v100, v168, v36
	v_fmac_f32_e32 v101, v169, v37
	v_lshlrev_b32_e32 v166, 16, v148
	v_and_b32_e32 v167, 0xffff0000, v148
	v_lshlrev_b32_e32 v168, 16, v149
	v_and_b32_e32 v169, 0xffff0000, v149
	v_fmac_f32_e32 v102, v166, v38
	v_fmac_f32_e32 v103, v167, v39
	v_fmac_f32_e32 v104, v168, v40
	v_fmac_f32_e32 v105, v169, v41
	v_lshlrev_b32_e32 v166, 16, v150
	v_and_b32_e32 v167, 0xffff0000, v150
	v_lshlrev_b32_e32 v168, 16, v151
	v_and_b32_e32 v169, 0xffff0000, v151
	v_fmac_f32_e32 v106, v166, v42
	v_fmac_f32_e32 v107, v167, v43
	v_fmac_f32_e32 v108, v168, v44
	v_fmac_f32_e32 v109, v169, v45
	v_lshlrev_b32_e32 v166, 16, v152
	v_and_b32_e32 v167, 0xffff0000, v152
	v_lshlrev_b32_e32 v168, 16, v153
	v_and_b32_e32 v169, 0xffff0000, v153
	v_fmac_f32_e32 v110, v166, v46
	v_fmac_f32_e32 v111, v167, v47
	v_fmac_f32_e32 v112, v168, v48
	v_fmac_f32_e32 v113, v169, v49
	v_lshlrev_b32_e32 v166, 16, v154
	v_and_b32_e32 v167, 0xffff0000, v154
	v_lshlrev_b32_e32 v168, 16, v155
	v_and_b32_e32 v169, 0xffff0000, v155
	v_fmac_f32_e32 v114, v166, v50
	v_fmac_f32_e32 v115, v167, v51
	v_fmac_f32_e32 v116, v168, v52
	v_fmac_f32_e32 v117, v169, v53
	v_lshlrev_b32_e32 v166, 16, v156
	v_and_b32_e32 v167, 0xffff0000, v156
	v_lshlrev_b32_e32 v168, 16, v157
	v_and_b32_e32 v169, 0xffff0000, v157
	v_fmac_f32_e32 v118, v166, v54
	v_fmac_f32_e32 v119, v167, v55
	v_fmac_f32_e32 v120, v168, v56
	v_fmac_f32_e32 v121, v169, v57
	v_lshlrev_b32_e32 v166, 16, v158
	v_and_b32_e32 v167, 0xffff0000, v158
	v_lshlrev_b32_e32 v168, 16, v159
	v_and_b32_e32 v169, 0xffff0000, v159
	v_fmac_f32_e32 v122, v166, v58
	v_fmac_f32_e32 v123, v167, v59
	v_fmac_f32_e32 v124, v168, v60
	v_fmac_f32_e32 v125, v169, v61
	v_lshlrev_b32_e32 v166, 16, v160
	v_and_b32_e32 v167, 0xffff0000, v160
	v_lshlrev_b32_e32 v168, 16, v161
	v_and_b32_e32 v169, 0xffff0000, v161
	v_fmac_f32_e32 v126, v166, v62
	v_fmac_f32_e32 v127, v167, v63
	v_fmac_f32_e32 v128, v168, v64
	v_fmac_f32_e32 v129, v169, v65
	s_add_i32 s75, s75, 1
	s_cmp_lt_u32 s75, 3
	s_cbranch_scc1 .Lbr_loop
	v_add_u32_e32 v170, 0x100000, v249
	v_cvt_pk_bf16_f32 v66, v66, v67
	v_cvt_pk_bf16_f32 v67, v68, v69
	global_store_dwordx2 v249, v[66:67], s[22:23]
	v_cvt_pk_bf16_f32 v70, v70, v71
	v_cvt_pk_bf16_f32 v71, v72, v73
	global_store_dwordx2 v249, v[70:71], s[22:23] offset:32
	v_cvt_pk_bf16_f32 v74, v74, v75
	v_cvt_pk_bf16_f32 v75, v76, v77
	global_store_dwordx2 v170, v[74:75], s[22:23]
	v_cvt_pk_bf16_f32 v78, v78, v79
	v_cvt_pk_bf16_f32 v79, v80, v81
	global_store_dwordx2 v170, v[78:79], s[22:23] offset:32
	v_cvt_pk_bf16_f32 v82, v82, v83
	v_cvt_pk_bf16_f32 v83, v84, v85
	global_store_dwordx2 v249, v[82:83], s[22:23] offset:1024
	v_cvt_pk_bf16_f32 v86, v86, v87
	v_cvt_pk_bf16_f32 v87, v88, v89
	global_store_dwordx2 v249, v[86:87], s[22:23] offset:1056
	v_cvt_pk_bf16_f32 v90, v90, v91
	v_cvt_pk_bf16_f32 v91, v92, v93
	global_store_dwordx2 v170, v[90:91], s[22:23] offset:1024
	v_cvt_pk_bf16_f32 v94, v94, v95
	v_cvt_pk_bf16_f32 v95, v96, v97
	global_store_dwordx2 v170, v[94:95], s[22:23] offset:1056
	v_cvt_pk_bf16_f32 v98, v98, v99
	v_cvt_pk_bf16_f32 v99, v100, v101
	global_store_dwordx2 v249, v[98:99], s[22:23] offset:2048
	v_cvt_pk_bf16_f32 v102, v102, v103
	v_cvt_pk_bf16_f32 v103, v104, v105
	global_store_dwordx2 v249, v[102:103], s[22:23] offset:2080
	v_cvt_pk_bf16_f32 v106, v106, v107
	v_cvt_pk_bf16_f32 v107, v108, v109
	global_store_dwordx2 v170, v[106:107], s[22:23] offset:2048
	v_cvt_pk_bf16_f32 v110, v110, v111
	v_cvt_pk_bf16_f32 v111, v112, v113
	global_store_dwordx2 v170, v[110:111], s[22:23] offset:2080
	v_cvt_pk_bf16_f32 v114, v114, v115
	v_cvt_pk_bf16_f32 v115, v116, v117
	global_store_dwordx2 v249, v[114:115], s[22:23] offset:3072
	v_cvt_pk_bf16_f32 v118, v118, v119
	v_cvt_pk_bf16_f32 v119, v120, v121
	global_store_dwordx2 v249, v[118:119], s[22:23] offset:3104
	v_cvt_pk_bf16_f32 v122, v122, v123
	v_cvt_pk_bf16_f32 v123, v124, v125
	global_store_dwordx2 v170, v[122:123], s[22:23] offset:3072
	v_cvt_pk_bf16_f32 v126, v126, v127
	v_cvt_pk_bf16_f32 v127, v128, v129
	global_store_dwordx2 v170, v[126:127], s[22:23] offset:3104
	s_add_i32 s17, s17, s78
	s_add_i32 s43, s43, s95
	s_cmpk_gt_i32 s17, 0x3ff
	s_cbranch_scc0 .LBB1_262
